# pipelined 128x128 K-loops: first 4 MFMAs of the next block issued before the mid-step LDS drain + barrier
# speedup vs baseline: 1.0253x; 1.0037x over previous
.Lxk_166:
	ds_read_b128 v[220:223], v136
	ds_read_b128 v[224:227], v136 offset:2048
	ds_read_b128 v[228:231], v136 offset:4096
	ds_read_b128 v[232:235], v136 offset:6144
	ds_read_b128 v[236:239], v137 offset:16384
	ds_read_b128 v[240:243], v137 offset:18432
	ds_read_b128 v[244:247], v137 offset:20480
	ds_read_b128 v[248:251], v137 offset:22528
	s_waitcnt lgkmcnt(8)
	v_mfma_f32_16x16x32_bf16 v[124:127], v[154:157], v[138:141], v[124:127]
	s_add_i32 s9, s9, 2
	v_mfma_f32_16x16x32_bf16 v[120:123], v[158:161], v[138:141], v[120:123]
	s_min_u32 s11, s9, 60
	v_mfma_f32_16x16x32_bf16 v[116:119], v[162:165], v[138:141], v[116:119]
	s_lshl_b32 s56, s11, 7
	v_mfma_f32_16x16x32_bf16 v[112:115], v[166:169], v[138:141], v[112:115]
	s_min_u32 s11, s9, 59
	v_mfma_f32_16x16x32_bf16 v[108:111], v[154:157], v[142:145], v[108:111]
	s_waitcnt vmcnt(15)
	v_mfma_f32_16x16x32_bf16 v[104:107], v[158:161], v[142:145], v[104:107]
	ds_write_b128 v133, v[0:3] offset:32768
	v_mfma_f32_16x16x32_bf16 v[100:103], v[162:165], v[142:145], v[100:103]
	s_waitcnt vmcnt(11)
	v_mfma_f32_16x16x32_bf16 v[96:99], v[166:169], v[142:145], v[96:99]
	ds_write_b128 v133, v[8:11] offset:49152
	v_mfma_f32_16x16x32_bf16 v[92:95], v[154:157], v[146:149], v[92:95]
	ds_write_b128 v133, v[4:7] offset:36864
	v_mfma_f32_16x16x32_bf16 v[88:91], v[158:161], v[146:149], v[88:91]
	s_waitcnt vmcnt(10)
	v_mfma_f32_16x16x32_bf16 v[84:87], v[162:165], v[146:149], v[84:87]
	ds_write_b128 v133, v[12:15] offset:53248
	v_mfma_f32_16x16x32_bf16 v[80:83], v[166:169], v[146:149], v[80:83]
	ds_write_b128 v133, v[16:19] offset:40960
	v_mfma_f32_16x16x32_bf16 v[76:79], v[154:157], v[150:153], v[76:79]
	s_waitcnt vmcnt(9)
	v_mfma_f32_16x16x32_bf16 v[72:75], v[158:161], v[150:153], v[72:75]
	ds_write_b128 v133, v[20:23] offset:57344
	v_mfma_f32_16x16x32_bf16 v[68:71], v[162:165], v[150:153], v[68:71]
	ds_write_b128 v133, v[24:27] offset:45056
	v_mfma_f32_16x16x32_bf16 v[64:67], v[166:169], v[150:153], v[64:67]
	s_waitcnt vmcnt(8)
	ds_write_b128 v133, v[28:31] offset:61440
	s_waitcnt lgkmcnt(8)
	v_mfma_f32_16x16x32_bf16 v[124:127], v[236:239], v[220:223], v[124:127]
	v_mfma_f32_16x16x32_bf16 v[120:123], v[240:243], v[220:223], v[120:123]
	v_mfma_f32_16x16x32_bf16 v[116:119], v[244:247], v[220:223], v[116:119]
	v_mfma_f32_16x16x32_bf16 v[112:115], v[248:251], v[220:223], v[112:115]
	s_waitcnt lgkmcnt(0)
	s_barrier
	ds_read_b128 v[138:141], v134 offset:32768
	ds_read_b128 v[142:145], v134 offset:34816
	ds_read_b128 v[146:149], v134 offset:36864
	ds_read_b128 v[150:153], v134 offset:38912
	ds_read_b128 v[154:157], v135 offset:49152
	ds_read_b128 v[158:161], v135 offset:51200
	ds_read_b128 v[162:165], v135 offset:53248
	ds_read_b128 v[166:169], v135 offset:55296
	v_lshl_add_u64 v[24:25], v[128:129], 0, s[56:57]
	v_add_co_u32_e32 v4, vcc, s33, v24
	v_lshl_add_u64 v[28:29], v[130:131], 0, s[56:57]
	s_nop 0
	v_addc_co_u32_e32 v5, vcc, 0, v25, vcc
	v_add_co_u32_e32 v12, vcc, s33, v28
	v_mfma_f32_16x16x32_bf16 v[108:111], v[236:239], v[224:227], v[108:111]
	global_load_dwordx4 v[0:3], v[24:25], off offset:384
	v_mfma_f32_16x16x32_bf16 v[104:107], v[240:243], v[224:227], v[104:107]
	global_load_dwordx4 v[8:11], v[28:29], off offset:384
	v_addc_co_u32_e32 v13, vcc, 0, v29, vcc
	v_mfma_f32_16x16x32_bf16 v[100:103], v[244:247], v[224:227], v[100:103]
	v_add_co_u32_e32 v16, vcc, s12, v24
	v_mfma_f32_16x16x32_bf16 v[96:99], v[248:251], v[224:227], v[96:99]
	s_nop 0
	v_addc_co_u32_e32 v17, vcc, 0, v25, vcc
	v_add_co_u32_e32 v20, vcc, s12, v28
	v_mfma_f32_16x16x32_bf16 v[92:95], v[236:239], v[228:231], v[92:95]
	s_nop 0
	v_addc_co_u32_e32 v21, vcc, 0, v29, vcc
	v_add_co_u32_e32 v24, vcc, s13, v24
	v_mfma_f32_16x16x32_bf16 v[88:91], v[240:243], v[228:231], v[88:91]
	s_nop 0
	v_addc_co_u32_e32 v25, vcc, 0, v25, vcc
	v_mfma_f32_16x16x32_bf16 v[84:87], v[244:247], v[228:231], v[84:87]
	v_add_co_u32_e32 v28, vcc, s13, v28
	s_nop 1
	s_nop 0
	v_addc_co_u32_e32 v29, vcc, 0, v29, vcc
	v_mfma_f32_16x16x32_bf16 v[80:83], v[248:251], v[228:231], v[80:83]
	global_load_dwordx4 v[4:7], v[4:5], off offset:384
	v_mfma_f32_16x16x32_bf16 v[76:79], v[236:239], v[232:235], v[76:79]
	global_load_dwordx4 v[12:15], v[12:13], off offset:384
	s_lshl_b32 s56, s11, 7
	v_mfma_f32_16x16x32_bf16 v[72:75], v[240:243], v[232:235], v[72:75]
	global_load_dwordx4 v[16:19], v[16:17], off offset:384
	v_mfma_f32_16x16x32_bf16 v[68:71], v[244:247], v[232:235], v[68:71]
	global_load_dwordx4 v[20:23], v[20:21], off offset:384
	s_cmp_lt_u32 s9, 62
	v_mfma_f32_16x16x32_bf16 v[64:67], v[248:251], v[232:235], v[64:67]
	global_load_dwordx4 v[24:27], v[24:25], off offset:384
	global_load_dwordx4 v[28:31], v[28:29], off offset:384
	ds_read_b128 v[220:223], v136 offset:32768
	ds_read_b128 v[224:227], v136 offset:34816
	ds_read_b128 v[228:231], v136 offset:36864
	ds_read_b128 v[232:235], v136 offset:38912
	ds_read_b128 v[236:239], v137 offset:49152
	ds_read_b128 v[240:243], v137 offset:51200
	ds_read_b128 v[244:247], v137 offset:53248
	ds_read_b128 v[248:251], v137 offset:55296
	s_waitcnt lgkmcnt(8)
	v_mfma_f32_16x16x32_bf16 v[124:127], v[154:157], v[138:141], v[124:127]
	s_waitcnt vmcnt(15)
	v_mfma_f32_16x16x32_bf16 v[120:123], v[158:161], v[138:141], v[120:123]
	ds_write_b128 v133, v[32:35]
	v_mfma_f32_16x16x32_bf16 v[116:119], v[162:165], v[138:141], v[116:119]
	s_waitcnt vmcnt(14)
	v_mfma_f32_16x16x32_bf16 v[112:115], v[166:169], v[138:141], v[112:115]
	ds_write_b128 v133, v[36:39] offset:16384
	v_mfma_f32_16x16x32_bf16 v[108:111], v[154:157], v[142:145], v[108:111]
	s_waitcnt vmcnt(13)
	v_mfma_f32_16x16x32_bf16 v[104:107], v[158:161], v[142:145], v[104:107]
	ds_write_b128 v133, v[40:43] offset:4096
	v_mfma_f32_16x16x32_bf16 v[100:103], v[162:165], v[142:145], v[100:103]
	s_waitcnt vmcnt(12)
	v_mfma_f32_16x16x32_bf16 v[96:99], v[166:169], v[142:145], v[96:99]
	ds_write_b128 v133, v[44:47] offset:20480
	v_mfma_f32_16x16x32_bf16 v[92:95], v[154:157], v[146:149], v[92:95]
	s_waitcnt vmcnt(11)
	v_mfma_f32_16x16x32_bf16 v[88:91], v[158:161], v[146:149], v[88:91]
	ds_write_b128 v133, v[48:51] offset:8192
	v_mfma_f32_16x16x32_bf16 v[84:87], v[162:165], v[146:149], v[84:87]
	s_waitcnt vmcnt(10)
	v_mfma_f32_16x16x32_bf16 v[80:83], v[166:169], v[146:149], v[80:83]
	ds_write_b128 v133, v[52:55] offset:24576
	v_mfma_f32_16x16x32_bf16 v[76:79], v[154:157], v[150:153], v[76:79]
	s_waitcnt vmcnt(9)
	v_mfma_f32_16x16x32_bf16 v[72:75], v[158:161], v[150:153], v[72:75]
	ds_write_b128 v133, v[56:59] offset:12288
	v_mfma_f32_16x16x32_bf16 v[68:71], v[162:165], v[150:153], v[68:71]
	s_waitcnt vmcnt(8)
	v_mfma_f32_16x16x32_bf16 v[64:67], v[166:169], v[150:153], v[64:67]
	ds_write_b128 v133, v[60:63] offset:28672
	s_waitcnt lgkmcnt(8)
	v_mfma_f32_16x16x32_bf16 v[124:127], v[236:239], v[220:223], v[124:127]
	v_mfma_f32_16x16x32_bf16 v[120:123], v[240:243], v[220:223], v[120:123]
	v_mfma_f32_16x16x32_bf16 v[116:119], v[244:247], v[220:223], v[116:119]
	v_mfma_f32_16x16x32_bf16 v[112:115], v[248:251], v[220:223], v[112:115]
	s_waitcnt lgkmcnt(0)
	s_barrier
	ds_read_b128 v[138:141], v134
	ds_read_b128 v[142:145], v134 offset:2048
	ds_read_b128 v[146:149], v134 offset:4096
	ds_read_b128 v[150:153], v134 offset:6144
	ds_read_b128 v[154:157], v135 offset:16384
	ds_read_b128 v[158:161], v135 offset:18432
	ds_read_b128 v[162:165], v135 offset:20480
	ds_read_b128 v[166:169], v135 offset:22528
	v_lshl_add_u64 v[56:57], v[128:129], 0, s[56:57]
	v_add_co_u32_e32 v40, vcc, s33, v56
	v_lshl_add_u64 v[60:61], v[130:131], 0, s[56:57]
	s_nop 0
	v_addc_co_u32_e32 v41, vcc, 0, v57, vcc
	v_add_co_u32_e32 v44, vcc, s33, v60
	v_mfma_f32_16x16x32_bf16 v[108:111], v[236:239], v[224:227], v[108:111]
	global_load_dwordx4 v[32:35], v[56:57], off offset:512
	global_load_dwordx4 v[36:39], v[60:61], off offset:512
	v_mfma_f32_16x16x32_bf16 v[104:107], v[240:243], v[224:227], v[104:107]
	v_addc_co_u32_e32 v45, vcc, 0, v61, vcc
	v_add_co_u32_e32 v48, vcc, s12, v56
	v_mfma_f32_16x16x32_bf16 v[100:103], v[244:247], v[224:227], v[100:103]
	global_load_dwordx4 v[40:43], v[40:41], off offset:512
	v_mfma_f32_16x16x32_bf16 v[96:99], v[248:251], v[224:227], v[96:99]
	s_nop 0
	v_addc_co_u32_e32 v49, vcc, 0, v57, vcc
	v_mfma_f32_16x16x32_bf16 v[92:95], v[236:239], v[228:231], v[92:95]
	v_add_co_u32_e32 v52, vcc, s12, v60
	global_load_dwordx4 v[44:47], v[44:45], off offset:512
	v_mfma_f32_16x16x32_bf16 v[88:91], v[240:243], v[228:231], v[88:91]
	s_nop 0
	v_mfma_f32_16x16x32_bf16 v[84:87], v[244:247], v[228:231], v[84:87]
	v_addc_co_u32_e32 v53, vcc, 0, v61, vcc
	v_add_co_u32_e32 v56, vcc, s13, v56
	v_mfma_f32_16x16x32_bf16 v[80:83], v[248:251], v[228:231], v[80:83]
	global_load_dwordx4 v[48:51], v[48:49], off offset:512
	s_nop 0
	v_mfma_f32_16x16x32_bf16 v[76:79], v[236:239], v[232:235], v[76:79]
	v_addc_co_u32_e32 v57, vcc, 0, v57, vcc
	v_mfma_f32_16x16x32_bf16 v[72:75], v[240:243], v[232:235], v[72:75]
	v_add_co_u32_e32 v60, vcc, s13, v60
	global_load_dwordx4 v[52:55], v[52:53], off offset:512
	v_mfma_f32_16x16x32_bf16 v[68:71], v[244:247], v[232:235], v[68:71]
	s_nop 0
	v_addc_co_u32_e32 v61, vcc, 0, v61, vcc
	v_mfma_f32_16x16x32_bf16 v[64:67], v[248:251], v[232:235], v[64:67]
	global_load_dwordx4 v[56:59], v[56:57], off offset:512
	global_load_dwordx4 v[60:63], v[60:61], off offset:512
	s_cbranch_scc1 .Lxk_166
	s_waitcnt vmcnt(0) lgkmcnt(0)
	s_waitcnt vmcnt(14)
	v_mov_b32_e32 v11, v192
	s_lshl_b32 s9, s10, 7
	v_lshlrev_b32_e32 v2, 8, v11
	v_and_b32_e32 v0, 15, v11
	v_bfe_u32 v1, v11, 4, 2
	v_and_b32_e32 v10, 0xffffc000, v2
	v_lshl_or_b32 v2, v0, 8, v10
	v_bitop3_b32 v3, v1, v11, 15 bitop3:0x78
	s_waitcnt vmcnt(13)
	v_bitop3_b32 v4, v1, v0, 4 bitop3:0x36
	v_bitop3_b32 v5, v1, v0, 8 bitop3:0x36
	v_bitop3_b32 v0, v1, v0, 12 bitop3:0x36
	v_lshl_or_b32 v3, v3, 4, v2
	v_lshl_or_b32 v4, v4, 4, v2
	v_lshl_or_b32 v5, v5, 4, v2
	v_lshl_or_b32 v0, v0, 4, v2
	s_waitcnt vmcnt(12)
	v_and_b32_e32 v12, 7, v11
	ds_write_b128 v3, v[124:127]
	ds_write_b128 v4, v[120:123]
	ds_write_b128 v5, v[116:119]
	ds_write_b128 v0, v[112:115]
	ds_write_b128 v3, v[108:111] offset:4096
	ds_write_b128 v4, v[104:107] offset:4096
	ds_write_b128 v5, v[100:103] offset:4096
	ds_write_b128 v0, v[96:99] offset:4096
	ds_write_b128 v3, v[92:95] offset:8192
	ds_write_b128 v4, v[88:91] offset:8192
	ds_write_b128 v5, v[84:87] offset:8192
	ds_write_b128 v0, v[80:83] offset:8192
	ds_write_b128 v3, v[76:79] offset:12288
	ds_write_b128 v4, v[72:75] offset:12288
	ds_write_b128 v5, v[68:71] offset:12288
	ds_write_b128 v0, v[64:67] offset:12288
	v_and_b32_e32 v0, 64, v11
	v_lshlrev_b32_e32 v1, 3, v12
	v_or3_b32 v8, v0, s9, v1
	s_andn2_b64 vcc, exec, s[6:7]
	v_ashrrev_i32_e32 v9, 31, v8
	s_movk_i32 s10, 0x401f
	s_cbranch_vccz .LBB0_159
	v_mov_b32_e32 v0, 0
	v_mov_b32_e32 v1, 0
	v_mov_b32_e32 v2, 0
	v_mov_b32_e32 v3, 0
	v_mov_b32_e32 v4, 0
	v_mov_b32_e32 v5, 0
	v_mov_b32_e32 v6, 0
	v_mov_b32_e32 v7, 0
	s_branch .LBB0_160

.Lxk_206:
	ds_read_b128 v[220:223], v136
	ds_read_b128 v[224:227], v136 offset:2048
	ds_read_b128 v[228:231], v136 offset:4096
	ds_read_b128 v[232:235], v136 offset:6144
	ds_read_b128 v[236:239], v137 offset:16384
	ds_read_b128 v[240:243], v137 offset:18432
	ds_read_b128 v[244:247], v137 offset:20480
	ds_read_b128 v[248:251], v137 offset:22528
	s_waitcnt lgkmcnt(8)
	v_mfma_f32_16x16x32_bf16 v[124:127], v[154:157], v[138:141], v[124:127]
	s_add_i32 s5, s5, 2
	v_mfma_f32_16x16x32_bf16 v[120:123], v[158:161], v[138:141], v[120:123]
	s_min_u32 s7, s5, 12
	v_mfma_f32_16x16x32_bf16 v[116:119], v[162:165], v[138:141], v[116:119]
	s_lshl_b32 s56, s7, 7
	v_mfma_f32_16x16x32_bf16 v[112:115], v[166:169], v[138:141], v[112:115]
	s_min_u32 s7, s5, 11
	v_mfma_f32_16x16x32_bf16 v[108:111], v[154:157], v[142:145], v[108:111]
	s_waitcnt vmcnt(15)
	v_mfma_f32_16x16x32_bf16 v[104:107], v[158:161], v[142:145], v[104:107]
	ds_write_b128 v133, v[0:3] offset:32768
	v_mfma_f32_16x16x32_bf16 v[100:103], v[162:165], v[142:145], v[100:103]
	s_waitcnt vmcnt(11)
	v_mfma_f32_16x16x32_bf16 v[96:99], v[166:169], v[142:145], v[96:99]
	ds_write_b128 v133, v[8:11] offset:49152
	v_mfma_f32_16x16x32_bf16 v[92:95], v[154:157], v[146:149], v[92:95]
	ds_write_b128 v133, v[4:7] offset:36864
	v_mfma_f32_16x16x32_bf16 v[88:91], v[158:161], v[146:149], v[88:91]
	s_waitcnt vmcnt(10)
	v_mfma_f32_16x16x32_bf16 v[84:87], v[162:165], v[146:149], v[84:87]
	ds_write_b128 v133, v[12:15] offset:53248
	v_mfma_f32_16x16x32_bf16 v[80:83], v[166:169], v[146:149], v[80:83]
	ds_write_b128 v133, v[16:19] offset:40960
	v_mfma_f32_16x16x32_bf16 v[76:79], v[154:157], v[150:153], v[76:79]
	s_waitcnt vmcnt(9)
	v_mfma_f32_16x16x32_bf16 v[72:75], v[158:161], v[150:153], v[72:75]
	ds_write_b128 v133, v[20:23] offset:57344
	v_mfma_f32_16x16x32_bf16 v[68:71], v[162:165], v[150:153], v[68:71]
	ds_write_b128 v133, v[24:27] offset:45056
	v_mfma_f32_16x16x32_bf16 v[64:67], v[166:169], v[150:153], v[64:67]
	s_waitcnt vmcnt(8)
	ds_write_b128 v133, v[28:31] offset:61440
	s_waitcnt lgkmcnt(8)
	v_mfma_f32_16x16x32_bf16 v[124:127], v[236:239], v[220:223], v[124:127]
	v_mfma_f32_16x16x32_bf16 v[120:123], v[240:243], v[220:223], v[120:123]
	v_mfma_f32_16x16x32_bf16 v[116:119], v[244:247], v[220:223], v[116:119]
	v_mfma_f32_16x16x32_bf16 v[112:115], v[248:251], v[220:223], v[112:115]
	s_waitcnt lgkmcnt(0)
	s_barrier
	ds_read_b128 v[138:141], v134 offset:32768
	ds_read_b128 v[142:145], v134 offset:34816
	ds_read_b128 v[146:149], v134 offset:36864
	ds_read_b128 v[150:153], v134 offset:38912
	ds_read_b128 v[154:157], v135 offset:49152
	ds_read_b128 v[158:161], v135 offset:51200
	ds_read_b128 v[162:165], v135 offset:53248
	ds_read_b128 v[166:169], v135 offset:55296
	v_lshl_add_u64 v[24:25], v[128:129], 0, s[56:57]
	v_add_co_u32_e32 v4, vcc, s65, v24
	v_lshl_add_u64 v[28:29], v[130:131], 0, s[56:57]
	s_nop 0
	v_addc_co_u32_e32 v5, vcc, 0, v25, vcc
	v_add_co_u32_e32 v12, vcc, s65, v28
	v_mfma_f32_16x16x32_bf16 v[108:111], v[236:239], v[224:227], v[108:111]
	global_load_dwordx4 v[0:3], v[24:25], off offset:384
	v_mfma_f32_16x16x32_bf16 v[104:107], v[240:243], v[224:227], v[104:107]
	global_load_dwordx4 v[8:11], v[28:29], off offset:384
	v_addc_co_u32_e32 v13, vcc, 0, v29, vcc
	v_mfma_f32_16x16x32_bf16 v[100:103], v[244:247], v[224:227], v[100:103]
	v_add_co_u32_e32 v16, vcc, s46, v24
	v_mfma_f32_16x16x32_bf16 v[96:99], v[248:251], v[224:227], v[96:99]
	s_nop 0
	v_addc_co_u32_e32 v17, vcc, 0, v25, vcc
	v_add_co_u32_e32 v20, vcc, s46, v28
	v_mfma_f32_16x16x32_bf16 v[92:95], v[236:239], v[228:231], v[92:95]
	s_nop 0
	v_addc_co_u32_e32 v21, vcc, 0, v29, vcc
	v_add_co_u32_e32 v24, vcc, s47, v24
	v_mfma_f32_16x16x32_bf16 v[88:91], v[240:243], v[228:231], v[88:91]
	s_nop 0
	v_addc_co_u32_e32 v25, vcc, 0, v25, vcc
	v_mfma_f32_16x16x32_bf16 v[84:87], v[244:247], v[228:231], v[84:87]
	v_add_co_u32_e32 v28, vcc, s47, v28
	s_nop 1
	s_nop 0
	v_addc_co_u32_e32 v29, vcc, 0, v29, vcc
	v_mfma_f32_16x16x32_bf16 v[80:83], v[248:251], v[228:231], v[80:83]
	global_load_dwordx4 v[4:7], v[4:5], off offset:384
	v_mfma_f32_16x16x32_bf16 v[76:79], v[236:239], v[232:235], v[76:79]
	global_load_dwordx4 v[12:15], v[12:13], off offset:384
	s_lshl_b32 s56, s7, 7
	v_mfma_f32_16x16x32_bf16 v[72:75], v[240:243], v[232:235], v[72:75]
	global_load_dwordx4 v[16:19], v[16:17], off offset:384
	v_mfma_f32_16x16x32_bf16 v[68:71], v[244:247], v[232:235], v[68:71]
	global_load_dwordx4 v[20:23], v[20:21], off offset:384
	s_cmp_lt_u32 s5, 14
	v_mfma_f32_16x16x32_bf16 v[64:67], v[248:251], v[232:235], v[64:67]
	global_load_dwordx4 v[24:27], v[24:25], off offset:384
	global_load_dwordx4 v[28:31], v[28:29], off offset:384
	ds_read_b128 v[220:223], v136 offset:32768
	ds_read_b128 v[224:227], v136 offset:34816
	ds_read_b128 v[228:231], v136 offset:36864
	ds_read_b128 v[232:235], v136 offset:38912
	ds_read_b128 v[236:239], v137 offset:49152
	ds_read_b128 v[240:243], v137 offset:51200
	ds_read_b128 v[244:247], v137 offset:53248
	ds_read_b128 v[248:251], v137 offset:55296
	s_waitcnt lgkmcnt(8)
	v_mfma_f32_16x16x32_bf16 v[124:127], v[154:157], v[138:141], v[124:127]
	s_waitcnt vmcnt(15)
	v_mfma_f32_16x16x32_bf16 v[120:123], v[158:161], v[138:141], v[120:123]
	ds_write_b128 v133, v[32:35]
	v_mfma_f32_16x16x32_bf16 v[116:119], v[162:165], v[138:141], v[116:119]
	s_waitcnt vmcnt(14)
	v_mfma_f32_16x16x32_bf16 v[112:115], v[166:169], v[138:141], v[112:115]
	ds_write_b128 v133, v[36:39] offset:16384
	v_mfma_f32_16x16x32_bf16 v[108:111], v[154:157], v[142:145], v[108:111]
	s_waitcnt vmcnt(13)
	v_mfma_f32_16x16x32_bf16 v[104:107], v[158:161], v[142:145], v[104:107]
	ds_write_b128 v133, v[40:43] offset:4096
	v_mfma_f32_16x16x32_bf16 v[100:103], v[162:165], v[142:145], v[100:103]
	s_waitcnt vmcnt(12)
	v_mfma_f32_16x16x32_bf16 v[96:99], v[166:169], v[142:145], v[96:99]
	ds_write_b128 v133, v[44:47] offset:20480
	v_mfma_f32_16x16x32_bf16 v[92:95], v[154:157], v[146:149], v[92:95]
	s_waitcnt vmcnt(11)
	v_mfma_f32_16x16x32_bf16 v[88:91], v[158:161], v[146:149], v[88:91]
	ds_write_b128 v133, v[48:51] offset:8192
	v_mfma_f32_16x16x32_bf16 v[84:87], v[162:165], v[146:149], v[84:87]
	s_waitcnt vmcnt(10)
	v_mfma_f32_16x16x32_bf16 v[80:83], v[166:169], v[146:149], v[80:83]
	ds_write_b128 v133, v[52:55] offset:24576
	v_mfma_f32_16x16x32_bf16 v[76:79], v[154:157], v[150:153], v[76:79]
	s_waitcnt vmcnt(9)
	v_mfma_f32_16x16x32_bf16 v[72:75], v[158:161], v[150:153], v[72:75]
	ds_write_b128 v133, v[56:59] offset:12288
	v_mfma_f32_16x16x32_bf16 v[68:71], v[162:165], v[150:153], v[68:71]
	s_waitcnt vmcnt(8)
	v_mfma_f32_16x16x32_bf16 v[64:67], v[166:169], v[150:153], v[64:67]
	ds_write_b128 v133, v[60:63] offset:28672
	s_waitcnt lgkmcnt(8)
	v_mfma_f32_16x16x32_bf16 v[124:127], v[236:239], v[220:223], v[124:127]
	v_mfma_f32_16x16x32_bf16 v[120:123], v[240:243], v[220:223], v[120:123]
	v_mfma_f32_16x16x32_bf16 v[116:119], v[244:247], v[220:223], v[116:119]
	v_mfma_f32_16x16x32_bf16 v[112:115], v[248:251], v[220:223], v[112:115]
	s_waitcnt lgkmcnt(0)
	s_barrier
	ds_read_b128 v[138:141], v134
	ds_read_b128 v[142:145], v134 offset:2048
	ds_read_b128 v[146:149], v134 offset:4096
	ds_read_b128 v[150:153], v134 offset:6144
	ds_read_b128 v[154:157], v135 offset:16384
	ds_read_b128 v[158:161], v135 offset:18432
	ds_read_b128 v[162:165], v135 offset:20480
	ds_read_b128 v[166:169], v135 offset:22528
	v_lshl_add_u64 v[56:57], v[128:129], 0, s[56:57]
	v_add_co_u32_e32 v40, vcc, s65, v56
	v_lshl_add_u64 v[60:61], v[130:131], 0, s[56:57]
	s_nop 0
	v_addc_co_u32_e32 v41, vcc, 0, v57, vcc
	v_add_co_u32_e32 v44, vcc, s65, v60
	v_mfma_f32_16x16x32_bf16 v[108:111], v[236:239], v[224:227], v[108:111]
	global_load_dwordx4 v[32:35], v[56:57], off offset:512
	global_load_dwordx4 v[36:39], v[60:61], off offset:512
	v_mfma_f32_16x16x32_bf16 v[104:107], v[240:243], v[224:227], v[104:107]
	v_addc_co_u32_e32 v45, vcc, 0, v61, vcc
	v_add_co_u32_e32 v48, vcc, s46, v56
	v_mfma_f32_16x16x32_bf16 v[100:103], v[244:247], v[224:227], v[100:103]
	global_load_dwordx4 v[40:43], v[40:41], off offset:512
	v_mfma_f32_16x16x32_bf16 v[96:99], v[248:251], v[224:227], v[96:99]
	s_nop 0
	v_addc_co_u32_e32 v49, vcc, 0, v57, vcc
	v_mfma_f32_16x16x32_bf16 v[92:95], v[236:239], v[228:231], v[92:95]
	v_add_co_u32_e32 v52, vcc, s46, v60
	global_load_dwordx4 v[44:47], v[44:45], off offset:512
	v_mfma_f32_16x16x32_bf16 v[88:91], v[240:243], v[228:231], v[88:91]
	s_nop 0
	v_mfma_f32_16x16x32_bf16 v[84:87], v[244:247], v[228:231], v[84:87]
	v_addc_co_u32_e32 v53, vcc, 0, v61, vcc
	v_add_co_u32_e32 v56, vcc, s47, v56
	v_mfma_f32_16x16x32_bf16 v[80:83], v[248:251], v[228:231], v[80:83]
	global_load_dwordx4 v[48:51], v[48:49], off offset:512
	s_nop 0
	v_mfma_f32_16x16x32_bf16 v[76:79], v[236:239], v[232:235], v[76:79]
	v_addc_co_u32_e32 v57, vcc, 0, v57, vcc
	v_mfma_f32_16x16x32_bf16 v[72:75], v[240:243], v[232:235], v[72:75]
	v_add_co_u32_e32 v60, vcc, s47, v60
	global_load_dwordx4 v[52:55], v[52:53], off offset:512
	v_mfma_f32_16x16x32_bf16 v[68:71], v[244:247], v[232:235], v[68:71]
	s_nop 0
	v_addc_co_u32_e32 v61, vcc, 0, v61, vcc
	v_mfma_f32_16x16x32_bf16 v[64:67], v[248:251], v[232:235], v[64:67]
	global_load_dwordx4 v[56:59], v[56:57], off offset:512
	global_load_dwordx4 v[60:63], v[60:61], off offset:512
	s_cbranch_scc1 .Lxk_206
	s_waitcnt vmcnt(0) lgkmcnt(0)
	s_waitcnt vmcnt(15)
	v_mov_b32_e32 v1, v192
	s_lshl_b32 s4, s4, 7
	v_lshlrev_b32_e32 v0, 8, v1
	v_and_b32_e32 v2, 15, v1
	v_bfe_u32 v3, v1, 4, 2
	v_and_b32_e32 v0, 0xffffc000, v0
	s_waitcnt vmcnt(13)
	v_lshl_or_b32 v4, v2, 8, v0
	v_bitop3_b32 v5, v3, v1, 15 bitop3:0x78
	v_bitop3_b32 v6, v3, v2, 4 bitop3:0x36
	v_bitop3_b32 v7, v3, v2, 8 bitop3:0x36
	v_bitop3_b32 v2, v3, v2, 12 bitop3:0x36
	v_lshl_or_b32 v5, v5, 4, v4
	v_lshl_or_b32 v6, v6, 4, v4
	v_lshl_or_b32 v7, v7, 4, v4
	v_lshl_or_b32 v2, v2, 4, v4
	ds_write_b128 v5, v[124:127]
	ds_write_b128 v6, v[120:123]
	ds_write_b128 v7, v[116:119]
	ds_write_b128 v2, v[112:115]
	ds_write_b128 v5, v[108:111] offset:4096
	ds_write_b128 v6, v[104:107] offset:4096
	ds_write_b128 v7, v[100:103] offset:4096
	ds_write_b128 v2, v[96:99] offset:4096
	ds_write_b128 v5, v[92:95] offset:8192
	ds_write_b128 v6, v[88:91] offset:8192
	ds_write_b128 v7, v[84:87] offset:8192
	ds_write_b128 v2, v[80:83] offset:8192
	ds_write_b128 v5, v[76:79] offset:12288
	ds_write_b128 v6, v[72:75] offset:12288
	ds_write_b128 v7, v[68:71] offset:12288
	ds_write_b128 v2, v[64:67] offset:12288
	v_and_b32_e32 v2, 7, v1
	v_and_b32_e32 v3, 64, v1
	v_lshlrev_b32_e32 v4, 3, v2
	v_or3_b32 v6, v3, s4, v4
	v_bfe_u32 v3, v1, 3, 3
	v_lshlrev_b32_e32 v2, 1, v2
	v_xor_b32_e32 v4, v3, v2
	v_lshl_or_b32 v8, v3, 8, v0
	v_lshlrev_b32_e32 v4, 4, v4
	v_or_b32_e32 v5, v8, v4
	s_waitcnt vmcnt(12)
	ds_read_b128 v[12:15], v5
	v_bitop3_b32 v5, v2, v3, 1 bitop3:0x36
	v_lshlrev_b32_e32 v5, 4, v5
	v_lshl_add_u32 v10, s6, 7, v132
	v_or_b32_e32 v8, v8, v5
	s_waitcnt vmcnt(11)
	ds_read_b128 v[16:19], v8
	v_or_b32_e32 v8, v3, v10
	v_ashrrev_i32_e32 v9, 31, v8
	v_ashrrev_i32_e32 v7, 31, v6
	v_lshlrev_b64 v[8:9], 11, v[8:9]
	s_waitcnt vmcnt(10)
	v_lshl_add_u64 v[20:21], s[2:3], 0, v[8:9]
	v_lshlrev_b64 v[8:9], 1, v[6:7]
	v_lshl_add_u64 v[6:7], v[20:21], 0, v[8:9]
	global_load_dwordx4 v[20:23], v[6:7], off
	v_or_b32_e32 v1, 1, v2
	s_add_i32 s11, s11, s10
	s_cmp_ge_i32 s11, s13
	s_waitcnt vmcnt(0)
	v_lshlrev_b32_e32 v11, 16, v20
	s_waitcnt lgkmcnt(1)
	v_fmamk_f32 v11, v11, 0x3fb504f3, v12
	v_and_b32_e32 v12, 0xffff0000, v20
	v_fmamk_f32 v12, v12, 0x3fb504f3, v13
	v_add_f32_e32 v11, 0, v11
	v_add_f32_e32 v12, 0, v12
	s_nop 1
	v_cvt_pk_bf16_f32 v12, v11, v12
	v_lshlrev_b32_e32 v11, 16, v21
	v_and_b32_e32 v13, 0xffff0000, v21
	v_fmamk_f32 v11, v11, 0x3fb504f3, v14
	v_fmac_f32_e32 v15, 0x3fb504f3, v13
	v_add_f32_e32 v11, 0, v11
	v_add_f32_e32 v13, 0, v15
	s_nop 1
	v_cvt_pk_bf16_f32 v13, v11, v13
	v_lshlrev_b32_e32 v11, 16, v22
	v_and_b32_e32 v14, 0xffff0000, v22
	s_waitcnt lgkmcnt(0)
	v_fmamk_f32 v11, v11, 0x3fb504f3, v16
	v_fmamk_f32 v14, v14, 0x3fb504f3, v17
	v_add_f32_e32 v11, 0, v11
	v_add_f32_e32 v14, 0, v14
	v_and_b32_e32 v15, 0xffff0000, v23
	s_nop 1
	v_cvt_pk_bf16_f32 v14, v11, v14
	v_lshlrev_b32_e32 v11, 16, v23
	v_fmac_f32_e32 v19, 0x3fb504f3, v15
	v_fmamk_f32 v11, v11, 0x3fb504f3, v18
	v_add_f32_e32 v15, 0, v19
	v_add_f32_e32 v11, 0, v11
	s_nop 1
	v_cvt_pk_bf16_f32 v15, v11, v15
	global_store_dwordx4 v[6:7], v[12:15], off
	v_or_b32_e32 v6, 8, v3
	v_lshl_or_b32 v7, v6, 8, v0
	v_bitop3_b32 v11, v3, v2, 8 bitop3:0x36
	v_lshl_or_b32 v11, v11, 4, v7
	ds_read_b128 v[12:15], v11
	v_bitop3_b32 v11, v3, v1, 8 bitop3:0x36
	v_lshl_or_b32 v7, v11, 4, v7
	v_or_b32_e32 v6, v6, v10
	ds_read_b128 v[16:19], v7
	v_ashrrev_i32_e32 v7, 31, v6
	v_lshlrev_b64 v[6:7], 11, v[6:7]
	v_lshl_add_u64 v[6:7], s[2:3], 0, v[6:7]
	v_lshl_add_u64 v[6:7], v[6:7], 0, v[8:9]
	global_load_dwordx4 v[20:23], v[6:7], off
	s_waitcnt vmcnt(0)
	v_lshlrev_b32_e32 v11, 16, v20
	s_waitcnt lgkmcnt(1)
	v_fmamk_f32 v11, v11, 0x3fb504f3, v12
	v_and_b32_e32 v12, 0xffff0000, v20
	v_fmamk_f32 v12, v12, 0x3fb504f3, v13
	v_add_f32_e32 v11, 0, v11
	v_add_f32_e32 v12, 0, v12
	s_nop 1
	v_cvt_pk_bf16_f32 v12, v11, v12
	v_lshlrev_b32_e32 v11, 16, v21
	v_and_b32_e32 v13, 0xffff0000, v21
	v_fmamk_f32 v11, v11, 0x3fb504f3, v14
	v_fmac_f32_e32 v15, 0x3fb504f3, v13
	v_add_f32_e32 v11, 0, v11
	v_add_f32_e32 v13, 0, v15
	s_nop 1
	v_cvt_pk_bf16_f32 v13, v11, v13
	v_lshlrev_b32_e32 v11, 16, v22
	v_and_b32_e32 v14, 0xffff0000, v22
	s_waitcnt lgkmcnt(0)
	v_fmamk_f32 v11, v11, 0x3fb504f3, v16
	v_fmamk_f32 v14, v14, 0x3fb504f3, v17
	v_add_f32_e32 v11, 0, v11
	v_add_f32_e32 v14, 0, v14
	v_and_b32_e32 v15, 0xffff0000, v23
	s_nop 1
	v_cvt_pk_bf16_f32 v14, v11, v14
	v_lshlrev_b32_e32 v11, 16, v23
	v_fmac_f32_e32 v19, 0x3fb504f3, v15
	v_fmamk_f32 v11, v11, 0x3fb504f3, v18
	v_add_f32_e32 v15, 0, v19
	v_add_f32_e32 v11, 0, v11
	s_nop 1
	v_cvt_pk_bf16_f32 v15, v11, v15
	global_store_dwordx4 v[6:7], v[12:15], off
	v_or_b32_e32 v6, 16, v3
	v_lshl_or_b32 v7, v6, 8, v0
	v_or_b32_e32 v11, v7, v4
	v_or_b32_e32 v7, v7, v5
	v_or_b32_e32 v6, v6, v10
	ds_read_b128 v[12:15], v11
	ds_read_b128 v[16:19], v7
	v_ashrrev_i32_e32 v7, 31, v6
	v_lshlrev_b64 v[6:7], 11, v[6:7]
	v_lshl_add_u64 v[6:7], s[2:3], 0, v[6:7]
	v_lshl_add_u64 v[6:7], v[6:7], 0, v[8:9]
	global_load_dwordx4 v[20:23], v[6:7], off
	s_waitcnt vmcnt(0)
	v_lshlrev_b32_e32 v11, 16, v20
	s_waitcnt lgkmcnt(1)
	v_fmamk_f32 v11, v11, 0x3fb504f3, v12
	v_and_b32_e32 v12, 0xffff0000, v20
	v_fmamk_f32 v12, v12, 0x3fb504f3, v13
	v_add_f32_e32 v11, 0, v11
	v_add_f32_e32 v12, 0, v12
	s_nop 1
	v_cvt_pk_bf16_f32 v12, v11, v12
	v_lshlrev_b32_e32 v11, 16, v21
	v_and_b32_e32 v13, 0xffff0000, v21
	v_fmamk_f32 v11, v11, 0x3fb504f3, v14
	v_fmac_f32_e32 v15, 0x3fb504f3, v13
	v_add_f32_e32 v11, 0, v11
	v_add_f32_e32 v13, 0, v15
	s_nop 1
	v_cvt_pk_bf16_f32 v13, v11, v13
	v_lshlrev_b32_e32 v11, 16, v22
	v_and_b32_e32 v14, 0xffff0000, v22
	s_waitcnt lgkmcnt(0)
	v_fmamk_f32 v11, v11, 0x3fb504f3, v16
	v_fmamk_f32 v14, v14, 0x3fb504f3, v17
	v_add_f32_e32 v11, 0, v11
	v_add_f32_e32 v14, 0, v14
	v_and_b32_e32 v15, 0xffff0000, v23
	s_nop 1
	v_cvt_pk_bf16_f32 v14, v11, v14
	v_lshlrev_b32_e32 v11, 16, v23
	v_fmac_f32_e32 v19, 0x3fb504f3, v15
	v_fmamk_f32 v11, v11, 0x3fb504f3, v18
	v_add_f32_e32 v15, 0, v19
	v_add_f32_e32 v11, 0, v11
	s_nop 1
	v_cvt_pk_bf16_f32 v15, v11, v15
	global_store_dwordx4 v[6:7], v[12:15], off
	v_or_b32_e32 v6, 24, v3
	v_lshl_or_b32 v7, v6, 8, v0
	v_bitop3_b32 v11, v6, v2, 15 bitop3:0x6c
	v_lshl_or_b32 v11, v11, 4, v7
	ds_read_b128 v[12:15], v11
	v_bitop3_b32 v11, v6, v1, 15 bitop3:0x6c
	v_lshl_or_b32 v7, v11, 4, v7
	v_or_b32_e32 v6, v6, v10
	ds_read_b128 v[16:19], v7
	v_ashrrev_i32_e32 v7, 31, v6
	v_lshlrev_b64 v[6:7], 11, v[6:7]
	v_lshl_add_u64 v[6:7], s[2:3], 0, v[6:7]
	v_lshl_add_u64 v[6:7], v[6:7], 0, v[8:9]
	global_load_dwordx4 v[20:23], v[6:7], off
	s_waitcnt vmcnt(0)
	v_lshlrev_b32_e32 v11, 16, v20
	s_waitcnt lgkmcnt(1)
	v_fmamk_f32 v11, v11, 0x3fb504f3, v12
	v_and_b32_e32 v12, 0xffff0000, v20
	v_fmamk_f32 v12, v12, 0x3fb504f3, v13
	v_add_f32_e32 v11, 0, v11
	v_add_f32_e32 v12, 0, v12
	s_nop 1
	v_cvt_pk_bf16_f32 v12, v11, v12
	v_lshlrev_b32_e32 v11, 16, v21
	v_and_b32_e32 v13, 0xffff0000, v21
	v_fmamk_f32 v11, v11, 0x3fb504f3, v14
	v_fmac_f32_e32 v15, 0x3fb504f3, v13
	v_add_f32_e32 v11, 0, v11
	v_add_f32_e32 v13, 0, v15
	s_nop 1
	v_cvt_pk_bf16_f32 v13, v11, v13
	v_lshlrev_b32_e32 v11, 16, v22
	v_and_b32_e32 v14, 0xffff0000, v22
	s_waitcnt lgkmcnt(0)
	v_fmamk_f32 v11, v11, 0x3fb504f3, v16
	v_fmamk_f32 v14, v14, 0x3fb504f3, v17
	v_add_f32_e32 v11, 0, v11
	v_add_f32_e32 v14, 0, v14
	v_and_b32_e32 v15, 0xffff0000, v23
	s_nop 1
	v_cvt_pk_bf16_f32 v14, v11, v14
	v_lshlrev_b32_e32 v11, 16, v23
	v_fmac_f32_e32 v19, 0x3fb504f3, v15
	v_fmamk_f32 v11, v11, 0x3fb504f3, v18
	v_add_f32_e32 v15, 0, v19
	v_add_f32_e32 v11, 0, v11
	s_nop 1
	v_cvt_pk_bf16_f32 v15, v11, v15
	global_store_dwordx4 v[6:7], v[12:15], off
	v_or_b32_e32 v6, 32, v3
	v_lshl_or_b32 v7, v6, 8, v0
	v_or_b32_e32 v11, v7, v4
	v_or_b32_e32 v7, v7, v5
	v_or_b32_e32 v6, v6, v10
	ds_read_b128 v[12:15], v11
	ds_read_b128 v[16:19], v7
	v_ashrrev_i32_e32 v7, 31, v6
	v_lshlrev_b64 v[6:7], 11, v[6:7]
	v_lshl_add_u64 v[6:7], s[2:3], 0, v[6:7]
	v_lshl_add_u64 v[6:7], v[6:7], 0, v[8:9]
	global_load_dwordx4 v[20:23], v[6:7], off
	s_waitcnt vmcnt(0)
	v_lshlrev_b32_e32 v11, 16, v20
	s_waitcnt lgkmcnt(1)
	v_fmamk_f32 v11, v11, 0x3fb504f3, v12
	v_and_b32_e32 v12, 0xffff0000, v20
	v_fmamk_f32 v12, v12, 0x3fb504f3, v13
	v_add_f32_e32 v11, 0, v11
	v_add_f32_e32 v12, 0, v12
	s_nop 1
	v_cvt_pk_bf16_f32 v12, v11, v12
	v_lshlrev_b32_e32 v11, 16, v21
	v_and_b32_e32 v13, 0xffff0000, v21
	v_fmamk_f32 v11, v11, 0x3fb504f3, v14
	v_fmac_f32_e32 v15, 0x3fb504f3, v13
	v_add_f32_e32 v11, 0, v11
	v_add_f32_e32 v13, 0, v15
	s_nop 1
	v_cvt_pk_bf16_f32 v13, v11, v13
	v_lshlrev_b32_e32 v11, 16, v22
	v_and_b32_e32 v14, 0xffff0000, v22
	s_waitcnt lgkmcnt(0)
	v_fmamk_f32 v11, v11, 0x3fb504f3, v16
	v_fmamk_f32 v14, v14, 0x3fb504f3, v17
	v_add_f32_e32 v11, 0, v11
	v_add_f32_e32 v14, 0, v14
	v_and_b32_e32 v15, 0xffff0000, v23
	s_nop 1
	v_cvt_pk_bf16_f32 v14, v11, v14
	v_lshlrev_b32_e32 v11, 16, v23
	v_fmac_f32_e32 v19, 0x3fb504f3, v15
	v_fmamk_f32 v11, v11, 0x3fb504f3, v18
	v_add_f32_e32 v15, 0, v19
	v_add_f32_e32 v11, 0, v11
	s_nop 1
	v_cvt_pk_bf16_f32 v15, v11, v15
	global_store_dwordx4 v[6:7], v[12:15], off
	v_or_b32_e32 v6, 40, v3
	v_lshl_or_b32 v7, v6, 8, v0
	v_bitop3_b32 v11, v6, v2, 15 bitop3:0x6c
	v_lshl_or_b32 v11, v11, 4, v7
	ds_read_b128 v[12:15], v11
	v_bitop3_b32 v11, v6, v1, 15 bitop3:0x6c
	v_lshl_or_b32 v7, v11, 4, v7
	v_or_b32_e32 v6, v6, v10
	ds_read_b128 v[16:19], v7
	v_ashrrev_i32_e32 v7, 31, v6
	v_lshlrev_b64 v[6:7], 11, v[6:7]
	v_lshl_add_u64 v[6:7], s[2:3], 0, v[6:7]
	v_lshl_add_u64 v[6:7], v[6:7], 0, v[8:9]
	global_load_dwordx4 v[20:23], v[6:7], off
	s_waitcnt vmcnt(0)
	v_lshlrev_b32_e32 v11, 16, v20
	s_waitcnt lgkmcnt(1)
	v_fmamk_f32 v11, v11, 0x3fb504f3, v12
	v_and_b32_e32 v12, 0xffff0000, v20
	v_fmamk_f32 v12, v12, 0x3fb504f3, v13
	v_add_f32_e32 v11, 0, v11
	v_add_f32_e32 v12, 0, v12
	s_nop 1
	v_cvt_pk_bf16_f32 v12, v11, v12
	v_lshlrev_b32_e32 v11, 16, v21
	v_and_b32_e32 v13, 0xffff0000, v21
	v_fmamk_f32 v11, v11, 0x3fb504f3, v14
	v_fmac_f32_e32 v15, 0x3fb504f3, v13
	v_add_f32_e32 v11, 0, v11
	v_add_f32_e32 v13, 0, v15
	s_nop 1
	v_cvt_pk_bf16_f32 v13, v11, v13
	v_lshlrev_b32_e32 v11, 16, v22
	v_and_b32_e32 v14, 0xffff0000, v22
	s_waitcnt lgkmcnt(0)
	v_fmamk_f32 v11, v11, 0x3fb504f3, v16
	v_fmamk_f32 v14, v14, 0x3fb504f3, v17
	v_add_f32_e32 v11, 0, v11
	v_add_f32_e32 v14, 0, v14
	s_nop 1
	v_cvt_pk_bf16_f32 v14, v11, v14
	v_lshlrev_b32_e32 v11, 16, v23
	v_and_b32_e32 v15, 0xffff0000, v23
	v_fmamk_f32 v11, v11, 0x3fb504f3, v18
	v_fmac_f32_e32 v19, 0x3fb504f3, v15
	v_add_f32_e32 v11, 0, v11
	v_add_f32_e32 v15, 0, v19
	s_nop 1
	v_cvt_pk_bf16_f32 v15, v11, v15
	v_or_b32_e32 v11, 48, v3
	v_or_b32_e32 v16, v11, v10
	v_ashrrev_i32_e32 v17, 31, v16
	v_lshlrev_b64 v[16:17], 11, v[16:17]
	v_lshl_add_u64 v[16:17], s[2:3], 0, v[16:17]
	v_lshl_add_u64 v[20:21], v[16:17], 0, v[8:9]
	global_load_dwordx4 v[16:19], v[20:21], off
	s_nop 0
	global_store_dwordx4 v[6:7], v[12:15], off
	v_lshl_or_b32 v6, v11, 8, v0
	v_or_b32_e32 v4, v6, v4
	ds_read_b128 v[12:15], v4
	v_or_b32_e32 v4, v6, v5
	ds_read_b128 v[4:7], v4
	s_waitcnt vmcnt(1)
	v_lshlrev_b32_e32 v11, 16, v16
	s_waitcnt lgkmcnt(1)
	v_fmamk_f32 v11, v11, 0x3fb504f3, v12
	v_and_b32_e32 v12, 0xffff0000, v16
	v_fmamk_f32 v12, v12, 0x3fb504f3, v13
	v_add_f32_e32 v11, 0, v11
	v_add_f32_e32 v12, 0, v12
	s_nop 1
	v_cvt_pk_bf16_f32 v12, v11, v12
	v_lshlrev_b32_e32 v11, 16, v17
	v_and_b32_e32 v13, 0xffff0000, v17
	v_fmamk_f32 v11, v11, 0x3fb504f3, v14
	v_fmac_f32_e32 v15, 0x3fb504f3, v13
	v_add_f32_e32 v11, 0, v11
	v_add_f32_e32 v13, 0, v15
	s_nop 1
	v_cvt_pk_bf16_f32 v13, v11, v13
	v_lshlrev_b32_e32 v11, 16, v18
	s_waitcnt lgkmcnt(0)
	v_fmamk_f32 v4, v11, 0x3fb504f3, v4
	v_and_b32_e32 v11, 0xffff0000, v18
	v_fmamk_f32 v5, v11, 0x3fb504f3, v5
	v_or_b32_e32 v11, 56, v3
	v_or_b32_e32 v10, v11, v10
	v_add_f32_e32 v4, 0, v4
	v_add_f32_e32 v5, 0, v5
	v_lshl_or_b32 v0, v11, 8, v0
	v_bitop3_b32 v2, v11, v2, 15 bitop3:0x6c
	v_bitop3_b32 v1, v11, v1, 15 bitop3:0x6c
	v_ashrrev_i32_e32 v11, 31, v10
	s_nop 1
	v_cvt_pk_bf16_f32 v14, v4, v5
	v_lshlrev_b32_e32 v4, 16, v19
	v_and_b32_e32 v5, 0xffff0000, v19
	v_lshlrev_b64 v[10:11], 11, v[10:11]
	v_fmamk_f32 v4, v4, 0x3fb504f3, v6
	v_fmac_f32_e32 v7, 0x3fb504f3, v5
	v_lshl_add_u64 v[10:11], s[2:3], 0, v[10:11]
	v_add_f32_e32 v4, 0, v4
	v_add_f32_e32 v5, 0, v7
	s_nop 1
	v_cvt_pk_bf16_f32 v15, v4, v5
	global_store_dwordx4 v[20:21], v[12:15], off
	v_lshl_or_b32 v2, v2, 4, v0
	ds_read_b128 v[4:7], v2
	v_lshl_add_u64 v[12:13], v[10:11], 0, v[8:9]
	global_load_dwordx4 v[8:11], v[12:13], off
	v_lshl_or_b32 v0, v1, 4, v0
	ds_read_b128 v[0:3], v0
	s_waitcnt vmcnt(0)
	v_lshlrev_b32_e32 v14, 16, v8
	v_and_b32_e32 v8, 0xffff0000, v8
	s_waitcnt lgkmcnt(1)
	v_fmamk_f32 v4, v14, 0x3fb504f3, v4
	v_fmamk_f32 v5, v8, 0x3fb504f3, v5
	v_add_f32_e32 v4, 0, v4
	v_add_f32_e32 v5, 0, v5
	s_nop 1
	v_cvt_pk_bf16_f32 v4, v4, v5
	v_lshlrev_b32_e32 v5, 16, v9
	v_fmamk_f32 v5, v5, 0x3fb504f3, v6
	v_and_b32_e32 v6, 0xffff0000, v9
	v_fmac_f32_e32 v7, 0x3fb504f3, v6
	v_add_f32_e32 v5, 0, v5
	v_add_f32_e32 v6, 0, v7
	s_nop 1
	v_cvt_pk_bf16_f32 v5, v5, v6
	v_lshlrev_b32_e32 v6, 16, v10
	s_waitcnt lgkmcnt(0)
	v_fmamk_f32 v0, v6, 0x3fb504f3, v0
	v_and_b32_e32 v6, 0xffff0000, v10
	v_fmamk_f32 v1, v6, 0x3fb504f3, v1
	v_add_f32_e32 v0, 0, v0
	v_add_f32_e32 v1, 0, v1
	s_nop 1
	v_cvt_pk_bf16_f32 v6, v0, v1
	v_lshlrev_b32_e32 v0, 16, v11
	v_and_b32_e32 v1, 0xffff0000, v11
	v_fmamk_f32 v0, v0, 0x3fb504f3, v2
	v_fmac_f32_e32 v3, 0x3fb504f3, v1
	v_add_f32_e32 v0, 0, v0
	v_add_f32_e32 v1, 0, v3
	s_nop 1
	v_cvt_pk_bf16_f32 v7, v0, v1
	global_store_dwordx4 v[12:13], v[4:7], off
	s_cbranch_scc0 .LBB0_201

.Lxk_222:
	ds_read_b128 v[194:197], v146
	ds_read_b128 v[198:201], v146 offset:2048
	ds_read_b128 v[202:205], v146 offset:4096
	ds_read_b128 v[206:209], v146 offset:6144
	ds_read_b128 v[210:213], v147 offset:16384
	ds_read_b128 v[214:217], v147 offset:18432
	ds_read_b128 v[244:247], v147 offset:20480
	ds_read_b128 v[248:251], v147 offset:22528
	s_waitcnt lgkmcnt(8)
	v_mfma_f32_16x16x32_bf16 v[124:127], v[164:167], v[148:151], v[124:127]
	s_add_i32 s7, s7, 2
	v_mfma_f32_16x16x32_bf16 v[120:123], v[168:171], v[148:151], v[120:123]
	s_min_u32 s18, s7, 12
	v_mfma_f32_16x16x32_bf16 v[116:119], v[172:175], v[148:151], v[116:119]
	s_lshl_b32 s56, s18, 7
	v_mfma_f32_16x16x32_bf16 v[112:115], v[178:181], v[148:151], v[112:115]
	s_min_u32 s18, s7, 11
	s_waitcnt vmcnt(15)
	v_mfma_f32_16x16x32_bf16 v[108:111], v[164:167], v[152:155], v[108:111]
	ds_write_b128 v143, v[0:3] offset:32768
	v_mfma_f32_16x16x32_bf16 v[104:107], v[168:171], v[152:155], v[104:107]
	s_waitcnt vmcnt(14)
	v_mfma_f32_16x16x32_bf16 v[100:103], v[172:175], v[152:155], v[100:103]
	ds_write_b128 v143, v[4:7] offset:49152
	v_mfma_f32_16x16x32_bf16 v[96:99], v[178:181], v[152:155], v[96:99]
	s_waitcnt vmcnt(13)
	ds_write_b128 v143, v[8:11] offset:36864
	v_mfma_f32_16x16x32_bf16 v[88:91], v[164:167], v[156:159], v[88:91]
	s_waitcnt vmcnt(12)
	v_mfma_f32_16x16x32_bf16 v[84:87], v[168:171], v[156:159], v[84:87]
	ds_write_b128 v143, v[12:15] offset:53248
	v_mfma_f32_16x16x32_bf16 v[72:75], v[172:175], v[156:159], v[72:75]
	s_waitcnt vmcnt(11)
	v_mfma_f32_16x16x32_bf16 v[64:67], v[178:181], v[156:159], v[64:67]
	ds_write_b128 v143, v[16:19] offset:40960
	s_waitcnt vmcnt(10)
	v_mfma_f32_16x16x32_bf16 v[52:55], v[164:167], v[160:163], v[52:55]
	ds_write_b128 v143, v[20:23] offset:57344
	v_mfma_f32_16x16x32_bf16 v[40:43], v[168:171], v[160:163], v[40:43]
	s_waitcnt vmcnt(9)
	v_mfma_f32_16x16x32_bf16 v[36:39], v[172:175], v[160:163], v[36:39]
	ds_write_b128 v143, v[28:31] offset:45056
	v_mfma_f32_16x16x32_bf16 v[24:27], v[178:181], v[160:163], v[24:27]
	s_waitcnt vmcnt(8)
	ds_write_b128 v143, v[32:35] offset:61440
	s_waitcnt lgkmcnt(8)
	v_mfma_f32_16x16x32_bf16 v[124:127], v[210:213], v[194:197], v[124:127]
	v_mfma_f32_16x16x32_bf16 v[120:123], v[214:217], v[194:197], v[120:123]
	v_mfma_f32_16x16x32_bf16 v[116:119], v[244:247], v[194:197], v[116:119]
	v_mfma_f32_16x16x32_bf16 v[112:115], v[248:251], v[194:197], v[112:115]
	s_waitcnt lgkmcnt(0)
	s_barrier
	ds_read_b128 v[148:151], v144 offset:32768
	ds_read_b128 v[152:155], v144 offset:34816
	ds_read_b128 v[156:159], v144 offset:36864
	ds_read_b128 v[160:163], v144 offset:38912
	ds_read_b128 v[164:167], v145 offset:49152
	ds_read_b128 v[168:171], v145 offset:51200
	ds_read_b128 v[172:175], v145 offset:53248
	ds_read_b128 v[178:181], v145 offset:55296
	v_lshl_add_u64 v[28:29], v[138:139], 0, s[56:57]
	v_add_co_u32_e32 v8, vcc, s65, v28
	v_lshl_add_u64 v[32:33], v[140:141], 0, s[56:57]
	s_nop 0
	v_addc_co_u32_e32 v9, vcc, 0, v29, vcc
	v_add_co_u32_e32 v12, vcc, s65, v32
	v_mfma_f32_16x16x32_bf16 v[108:111], v[210:213], v[198:201], v[108:111]
	global_load_dwordx4 v[0:3], v[28:29], off offset:384
	v_mfma_f32_16x16x32_bf16 v[104:107], v[214:217], v[198:201], v[104:107]
	global_load_dwordx4 v[4:7], v[32:33], off offset:384
	v_addc_co_u32_e32 v13, vcc, 0, v33, vcc
	v_mfma_f32_16x16x32_bf16 v[100:103], v[244:247], v[198:201], v[100:103]
	v_add_co_u32_e32 v16, vcc, s46, v28
	v_mfma_f32_16x16x32_bf16 v[96:99], v[248:251], v[198:201], v[96:99]
	s_nop 0
	v_addc_co_u32_e32 v17, vcc, 0, v29, vcc
	v_add_co_u32_e32 v20, vcc, s46, v32
	v_mfma_f32_16x16x32_bf16 v[88:91], v[210:213], v[202:205], v[88:91]
	s_nop 0
	v_addc_co_u32_e32 v21, vcc, 0, v33, vcc
	v_add_co_u32_e32 v28, vcc, s47, v28
	v_mfma_f32_16x16x32_bf16 v[84:87], v[214:217], v[202:205], v[84:87]
	s_nop 0
	v_addc_co_u32_e32 v29, vcc, 0, v29, vcc
	v_mfma_f32_16x16x32_bf16 v[72:75], v[244:247], v[202:205], v[72:75]
	v_add_co_u32_e32 v32, vcc, s47, v32
	s_nop 1
	s_nop 0
	v_addc_co_u32_e32 v33, vcc, 0, v33, vcc
	v_mfma_f32_16x16x32_bf16 v[64:67], v[248:251], v[202:205], v[64:67]
	global_load_dwordx4 v[8:11], v[8:9], off offset:384
	v_mfma_f32_16x16x32_bf16 v[52:55], v[210:213], v[206:209], v[52:55]
	global_load_dwordx4 v[12:15], v[12:13], off offset:384
	s_lshl_b32 s56, s18, 7
	v_mfma_f32_16x16x32_bf16 v[40:43], v[214:217], v[206:209], v[40:43]
	global_load_dwordx4 v[16:19], v[16:17], off offset:384
	v_mfma_f32_16x16x32_bf16 v[36:39], v[244:247], v[206:209], v[36:39]
	global_load_dwordx4 v[20:23], v[20:21], off offset:384
	s_cmp_lt_u32 s7, 14
	v_mfma_f32_16x16x32_bf16 v[24:27], v[248:251], v[206:209], v[24:27]
	global_load_dwordx4 v[28:31], v[28:29], off offset:384
	global_load_dwordx4 v[32:35], v[32:33], off offset:384
	ds_read_b128 v[194:197], v146 offset:32768
	ds_read_b128 v[198:201], v146 offset:34816
	ds_read_b128 v[202:205], v146 offset:36864
	ds_read_b128 v[206:209], v146 offset:38912
	ds_read_b128 v[210:213], v147 offset:49152
	ds_read_b128 v[214:217], v147 offset:51200
	ds_read_b128 v[244:247], v147 offset:53248
	ds_read_b128 v[248:251], v147 offset:55296
	s_waitcnt lgkmcnt(8)
	v_mfma_f32_16x16x32_bf16 v[124:127], v[164:167], v[148:151], v[124:127]
	s_waitcnt vmcnt(15)
	v_mfma_f32_16x16x32_bf16 v[120:123], v[168:171], v[148:151], v[120:123]
	ds_write_b128 v143, v[44:47]
	v_mfma_f32_16x16x32_bf16 v[116:119], v[172:175], v[148:151], v[116:119]
	s_waitcnt vmcnt(14)
	v_mfma_f32_16x16x32_bf16 v[112:115], v[178:181], v[148:151], v[112:115]
	ds_write_b128 v143, v[48:51] offset:16384
	v_mfma_f32_16x16x32_bf16 v[108:111], v[164:167], v[152:155], v[108:111]
	s_waitcnt vmcnt(13)
	v_mfma_f32_16x16x32_bf16 v[104:107], v[168:171], v[152:155], v[104:107]
	ds_write_b128 v143, v[56:59] offset:4096
	v_mfma_f32_16x16x32_bf16 v[100:103], v[172:175], v[152:155], v[100:103]
	s_waitcnt vmcnt(12)
	v_mfma_f32_16x16x32_bf16 v[96:99], v[178:181], v[152:155], v[96:99]
	ds_write_b128 v143, v[60:63] offset:20480
	v_mfma_f32_16x16x32_bf16 v[88:91], v[164:167], v[156:159], v[88:91]
	s_waitcnt vmcnt(11)
	v_mfma_f32_16x16x32_bf16 v[84:87], v[168:171], v[156:159], v[84:87]
	ds_write_b128 v143, v[68:71] offset:8192
	v_mfma_f32_16x16x32_bf16 v[72:75], v[172:175], v[156:159], v[72:75]
	s_waitcnt vmcnt(10)
	v_mfma_f32_16x16x32_bf16 v[64:67], v[178:181], v[156:159], v[64:67]
	ds_write_b128 v143, v[76:79] offset:24576
	v_mfma_f32_16x16x32_bf16 v[52:55], v[164:167], v[160:163], v[52:55]
	s_waitcnt vmcnt(9)
	v_mfma_f32_16x16x32_bf16 v[40:43], v[168:171], v[160:163], v[40:43]
	ds_write_b128 v143, v[80:83] offset:12288
	v_mfma_f32_16x16x32_bf16 v[36:39], v[172:175], v[160:163], v[36:39]
	s_waitcnt vmcnt(8)
	v_mfma_f32_16x16x32_bf16 v[24:27], v[178:181], v[160:163], v[24:27]
	ds_write_b128 v143, v[92:95] offset:28672
	s_waitcnt lgkmcnt(8)
	v_mfma_f32_16x16x32_bf16 v[124:127], v[210:213], v[194:197], v[124:127]
	v_mfma_f32_16x16x32_bf16 v[120:123], v[214:217], v[194:197], v[120:123]
	v_mfma_f32_16x16x32_bf16 v[116:119], v[244:247], v[194:197], v[116:119]
	v_mfma_f32_16x16x32_bf16 v[112:115], v[248:251], v[194:197], v[112:115]
	s_waitcnt lgkmcnt(0)
	s_barrier
	ds_read_b128 v[148:151], v144
	ds_read_b128 v[152:155], v144 offset:2048
	ds_read_b128 v[156:159], v144 offset:4096
	ds_read_b128 v[160:163], v144 offset:6144
	ds_read_b128 v[164:167], v145 offset:16384
	ds_read_b128 v[168:171], v145 offset:18432
	ds_read_b128 v[172:175], v145 offset:20480
	ds_read_b128 v[178:181], v145 offset:22528
	v_lshl_add_u64 v[80:81], v[138:139], 0, s[56:57]
	v_add_co_u32_e32 v56, vcc, s65, v80
	v_lshl_add_u64 v[92:93], v[140:141], 0, s[56:57]
	s_nop 0
	v_addc_co_u32_e32 v57, vcc, 0, v81, vcc
	v_add_co_u32_e32 v60, vcc, s65, v92
	v_mfma_f32_16x16x32_bf16 v[108:111], v[210:213], v[198:201], v[108:111]
	global_load_dwordx4 v[44:47], v[80:81], off offset:512
	global_load_dwordx4 v[48:51], v[92:93], off offset:512
	v_mfma_f32_16x16x32_bf16 v[104:107], v[214:217], v[198:201], v[104:107]
	v_addc_co_u32_e32 v61, vcc, 0, v93, vcc
	v_add_co_u32_e32 v68, vcc, s46, v80
	v_mfma_f32_16x16x32_bf16 v[100:103], v[244:247], v[198:201], v[100:103]
	global_load_dwordx4 v[56:59], v[56:57], off offset:512
	v_mfma_f32_16x16x32_bf16 v[96:99], v[248:251], v[198:201], v[96:99]
	s_nop 0
	v_addc_co_u32_e32 v69, vcc, 0, v81, vcc
	v_mfma_f32_16x16x32_bf16 v[88:91], v[210:213], v[202:205], v[88:91]
	v_add_co_u32_e32 v76, vcc, s46, v92
	global_load_dwordx4 v[60:63], v[60:61], off offset:512
	v_mfma_f32_16x16x32_bf16 v[84:87], v[214:217], v[202:205], v[84:87]
	s_nop 0
	v_mfma_f32_16x16x32_bf16 v[72:75], v[244:247], v[202:205], v[72:75]
	v_addc_co_u32_e32 v77, vcc, 0, v93, vcc
	v_add_co_u32_e32 v80, vcc, s47, v80
	v_mfma_f32_16x16x32_bf16 v[64:67], v[248:251], v[202:205], v[64:67]
	global_load_dwordx4 v[68:71], v[68:69], off offset:512
	s_nop 0
	v_mfma_f32_16x16x32_bf16 v[52:55], v[210:213], v[206:209], v[52:55]
	v_addc_co_u32_e32 v81, vcc, 0, v81, vcc
	v_mfma_f32_16x16x32_bf16 v[40:43], v[214:217], v[206:209], v[40:43]
	v_add_co_u32_e32 v92, vcc, s47, v92
	global_load_dwordx4 v[76:79], v[76:77], off offset:512
	v_mfma_f32_16x16x32_bf16 v[36:39], v[244:247], v[206:209], v[36:39]
	s_nop 0
	v_addc_co_u32_e32 v93, vcc, 0, v93, vcc
	v_mfma_f32_16x16x32_bf16 v[24:27], v[248:251], v[206:209], v[24:27]
	global_load_dwordx4 v[80:83], v[80:81], off offset:512
	global_load_dwordx4 v[92:95], v[92:93], off offset:512
	s_cbranch_scc1 .Lxk_222
	s_waitcnt vmcnt(0) lgkmcnt(0)
	s_waitcnt vmcnt(15)
	v_mul_f32_e32 v0, 0xbfb8aa3b, v124
	v_mul_f32_e32 v1, 0xbfb8aa3b, v125
	v_exp_f32_e32 v0, v0
	v_exp_f32_e32 v1, v1
	v_mul_f32_e32 v2, 0xbfb8aa3b, v126
	v_mul_f32_e32 v3, 0xbfb8aa3b, v127
	v_exp_f32_e32 v2, v2
	v_exp_f32_e32 v3, v3
	v_add_f32_e32 v0, 1.0, v0
	v_add_f32_e32 v1, 1.0, v1
	v_rcp_f32_e32 v0, v0
	v_rcp_f32_e32 v1, v1
	s_nop 1
	v_cvt_pk_bf16_f32 v173, v0, v1
	v_add_f32_e32 v0, 1.0, v2
	v_add_f32_e32 v1, 1.0, v3
	v_mul_f32_e32 v2, 0xbfb8aa3b, v120
	v_mul_f32_e32 v3, 0xbfb8aa3b, v121
	v_exp_f32_e32 v2, v2
	v_exp_f32_e32 v3, v3
	v_rcp_f32_e32 v0, v0
	v_rcp_f32_e32 v1, v1
	s_nop 1
	v_cvt_pk_bf16_f32 v174, v0, v1
	v_add_f32_e32 v0, 1.0, v2
	v_add_f32_e32 v1, 1.0, v3
	v_mul_f32_e32 v2, 0xbfb8aa3b, v122
	v_mul_f32_e32 v3, 0xbfb8aa3b, v123
	v_exp_f32_e32 v2, v2
	v_exp_f32_e32 v3, v3
	v_rcp_f32_e32 v0, v0
	v_rcp_f32_e32 v1, v1
	s_nop 1
	v_cvt_pk_bf16_f32 v171, v0, v1
	v_add_f32_e32 v0, 1.0, v2
	v_add_f32_e32 v1, 1.0, v3
	v_mul_f32_e32 v2, 0xbfb8aa3b, v116
	v_mul_f32_e32 v3, 0xbfb8aa3b, v117
	v_exp_f32_e32 v2, v2
	v_exp_f32_e32 v3, v3
	v_rcp_f32_e32 v0, v0
	v_rcp_f32_e32 v1, v1
	s_nop 1
	v_cvt_pk_bf16_f32 v172, v0, v1
	v_add_f32_e32 v0, 1.0, v2
	v_add_f32_e32 v1, 1.0, v3
	v_mul_f32_e32 v2, 0xbfb8aa3b, v118
	v_mul_f32_e32 v3, 0xbfb8aa3b, v119
	v_exp_f32_e32 v2, v2
	v_exp_f32_e32 v3, v3
	v_rcp_f32_e32 v0, v0
	v_rcp_f32_e32 v1, v1
	s_nop 1
	v_cvt_pk_bf16_f32 v169, v0, v1
	v_add_f32_e32 v0, 1.0, v2
	v_add_f32_e32 v1, 1.0, v3
	v_mul_f32_e32 v2, 0xbfb8aa3b, v112
	v_mul_f32_e32 v3, 0xbfb8aa3b, v113
	v_exp_f32_e32 v2, v2
	v_exp_f32_e32 v3, v3
	v_rcp_f32_e32 v0, v0
	v_rcp_f32_e32 v1, v1
	s_nop 1
	v_cvt_pk_bf16_f32 v170, v0, v1
	v_add_f32_e32 v0, 1.0, v2
	v_add_f32_e32 v1, 1.0, v3
	v_mul_f32_e32 v2, 0xbfb8aa3b, v114
	v_mul_f32_e32 v3, 0xbfb8aa3b, v115
	v_exp_f32_e32 v2, v2
	v_exp_f32_e32 v3, v3
	v_rcp_f32_e32 v0, v0
	v_rcp_f32_e32 v1, v1
	s_nop 1
	v_cvt_pk_bf16_f32 v167, v0, v1
	v_add_f32_e32 v0, 1.0, v2
	v_add_f32_e32 v1, 1.0, v3
	v_mul_f32_e32 v2, 0xbfb8aa3b, v108
	v_mul_f32_e32 v3, 0xbfb8aa3b, v109
	v_exp_f32_e32 v2, v2
	v_exp_f32_e32 v3, v3
	v_rcp_f32_e32 v0, v0
	v_rcp_f32_e32 v1, v1
	s_nop 1
	v_cvt_pk_bf16_f32 v168, v0, v1
	v_add_f32_e32 v0, 1.0, v2
	v_add_f32_e32 v1, 1.0, v3
	v_mul_f32_e32 v2, 0xbfb8aa3b, v110
	v_mul_f32_e32 v3, 0xbfb8aa3b, v111
	v_exp_f32_e32 v2, v2
	v_exp_f32_e32 v3, v3
	v_rcp_f32_e32 v0, v0
	v_rcp_f32_e32 v1, v1
	s_nop 1
	v_cvt_pk_bf16_f32 v165, v0, v1
	v_add_f32_e32 v0, 1.0, v2
	v_add_f32_e32 v1, 1.0, v3
	v_mul_f32_e32 v2, 0xbfb8aa3b, v104
	v_mul_f32_e32 v3, 0xbfb8aa3b, v105
	v_exp_f32_e32 v2, v2
	v_exp_f32_e32 v3, v3
	v_rcp_f32_e32 v0, v0
	v_rcp_f32_e32 v1, v1
	s_nop 1
	v_cvt_pk_bf16_f32 v166, v0, v1
	v_add_f32_e32 v0, 1.0, v2
	v_add_f32_e32 v1, 1.0, v3
	v_mul_f32_e32 v2, 0xbfb8aa3b, v106
	v_mul_f32_e32 v3, 0xbfb8aa3b, v107
	v_exp_f32_e32 v2, v2
	v_exp_f32_e32 v3, v3
	v_rcp_f32_e32 v0, v0
	v_rcp_f32_e32 v1, v1
	s_nop 1
	v_cvt_pk_bf16_f32 v163, v0, v1
	v_add_f32_e32 v0, 1.0, v2
	v_add_f32_e32 v1, 1.0, v3
	v_mul_f32_e32 v2, 0xbfb8aa3b, v100
	v_mul_f32_e32 v3, 0xbfb8aa3b, v101
	v_exp_f32_e32 v2, v2
	v_exp_f32_e32 v3, v3
	v_rcp_f32_e32 v0, v0
	v_rcp_f32_e32 v1, v1
	s_nop 1
	v_cvt_pk_bf16_f32 v164, v0, v1
	v_add_f32_e32 v0, 1.0, v2
	v_add_f32_e32 v1, 1.0, v3
	v_mul_f32_e32 v2, 0xbfb8aa3b, v102
	v_mul_f32_e32 v3, 0xbfb8aa3b, v103
	v_exp_f32_e32 v2, v2
	v_exp_f32_e32 v3, v3
	v_rcp_f32_e32 v0, v0
	v_rcp_f32_e32 v1, v1
	s_nop 1
	v_cvt_pk_bf16_f32 v161, v0, v1
	v_add_f32_e32 v0, 1.0, v2
	v_add_f32_e32 v1, 1.0, v3
	v_mul_f32_e32 v2, 0xbfb8aa3b, v96
	v_mul_f32_e32 v3, 0xbfb8aa3b, v97
	v_exp_f32_e32 v2, v2
	v_exp_f32_e32 v3, v3
	v_rcp_f32_e32 v0, v0
	v_rcp_f32_e32 v1, v1
	s_nop 1
	v_cvt_pk_bf16_f32 v162, v0, v1
	v_add_f32_e32 v0, 1.0, v2
	v_add_f32_e32 v1, 1.0, v3
	v_mul_f32_e32 v2, 0xbfb8aa3b, v98
	v_mul_f32_e32 v3, 0xbfb8aa3b, v99
	v_exp_f32_e32 v2, v2
	v_exp_f32_e32 v3, v3
	v_rcp_f32_e32 v0, v0
	v_rcp_f32_e32 v1, v1
	s_nop 1
	v_cvt_pk_bf16_f32 v159, v0, v1
	v_add_f32_e32 v0, 1.0, v2
	v_add_f32_e32 v1, 1.0, v3
	v_mul_f32_e32 v2, 0xbfb8aa3b, v88
	v_mul_f32_e32 v3, 0xbfb8aa3b, v89
	v_exp_f32_e32 v2, v2
	v_exp_f32_e32 v3, v3
	v_rcp_f32_e32 v0, v0
	v_rcp_f32_e32 v1, v1
	s_nop 1
	v_cvt_pk_bf16_f32 v160, v0, v1
	v_add_f32_e32 v0, 1.0, v2
	v_add_f32_e32 v1, 1.0, v3
	v_mul_f32_e32 v2, 0xbfb8aa3b, v90
	v_mul_f32_e32 v3, 0xbfb8aa3b, v91
	v_exp_f32_e32 v2, v2
	v_exp_f32_e32 v3, v3
	v_rcp_f32_e32 v0, v0
	v_rcp_f32_e32 v1, v1
	s_nop 1
	v_cvt_pk_bf16_f32 v157, v0, v1
	v_add_f32_e32 v0, 1.0, v2
	v_add_f32_e32 v1, 1.0, v3
	v_mul_f32_e32 v2, 0xbfb8aa3b, v84
	v_mul_f32_e32 v3, 0xbfb8aa3b, v85
	v_exp_f32_e32 v2, v2
	v_exp_f32_e32 v3, v3
	v_rcp_f32_e32 v0, v0
	v_rcp_f32_e32 v1, v1
	s_nop 1
	v_cvt_pk_bf16_f32 v158, v0, v1
	v_add_f32_e32 v0, 1.0, v2
	v_add_f32_e32 v1, 1.0, v3
	v_mul_f32_e32 v2, 0xbfb8aa3b, v86
	v_mul_f32_e32 v3, 0xbfb8aa3b, v87
	v_exp_f32_e32 v2, v2
	v_exp_f32_e32 v3, v3
	v_rcp_f32_e32 v0, v0
	v_rcp_f32_e32 v1, v1
	s_nop 1
	v_cvt_pk_bf16_f32 v155, v0, v1
	v_add_f32_e32 v0, 1.0, v2
	v_add_f32_e32 v1, 1.0, v3
	v_mul_f32_e32 v2, 0xbfb8aa3b, v72
	v_mul_f32_e32 v3, 0xbfb8aa3b, v73
	v_exp_f32_e32 v2, v2
	v_exp_f32_e32 v3, v3
	v_rcp_f32_e32 v0, v0
	v_rcp_f32_e32 v1, v1
	s_nop 1
	v_cvt_pk_bf16_f32 v156, v0, v1
	v_add_f32_e32 v0, 1.0, v2
	v_add_f32_e32 v1, 1.0, v3
	v_mul_f32_e32 v2, 0xbfb8aa3b, v74
	v_mul_f32_e32 v3, 0xbfb8aa3b, v75
	v_exp_f32_e32 v2, v2
	v_exp_f32_e32 v3, v3
	v_rcp_f32_e32 v0, v0
	v_rcp_f32_e32 v1, v1
	s_nop 1
	v_cvt_pk_bf16_f32 v153, v0, v1
	v_add_f32_e32 v0, 1.0, v2
	v_add_f32_e32 v1, 1.0, v3
	v_mul_f32_e32 v2, 0xbfb8aa3b, v64
	v_mul_f32_e32 v3, 0xbfb8aa3b, v65
	v_exp_f32_e32 v2, v2
	v_exp_f32_e32 v3, v3
	v_rcp_f32_e32 v0, v0
	v_rcp_f32_e32 v1, v1
	s_nop 1
	v_cvt_pk_bf16_f32 v154, v0, v1
	v_add_f32_e32 v0, 1.0, v2
	v_add_f32_e32 v1, 1.0, v3
	v_mul_f32_e32 v2, 0xbfb8aa3b, v66
	v_mul_f32_e32 v3, 0xbfb8aa3b, v67
	v_exp_f32_e32 v2, v2
	v_exp_f32_e32 v3, v3
	v_rcp_f32_e32 v0, v0
	v_rcp_f32_e32 v1, v1
	s_nop 1
	v_cvt_pk_bf16_f32 v151, v0, v1
	v_add_f32_e32 v0, 1.0, v2
	v_add_f32_e32 v1, 1.0, v3
	v_mul_f32_e32 v2, 0xbfb8aa3b, v52
	v_mul_f32_e32 v3, 0xbfb8aa3b, v53
	v_exp_f32_e32 v2, v2
	v_exp_f32_e32 v3, v3
	v_rcp_f32_e32 v0, v0
	v_rcp_f32_e32 v1, v1
	s_nop 1
	v_cvt_pk_bf16_f32 v152, v0, v1
	v_add_f32_e32 v0, 1.0, v2
	v_add_f32_e32 v1, 1.0, v3
	v_mul_f32_e32 v2, 0xbfb8aa3b, v54
	v_mul_f32_e32 v3, 0xbfb8aa3b, v55
	v_exp_f32_e32 v2, v2
	v_exp_f32_e32 v3, v3
	v_rcp_f32_e32 v0, v0
	v_rcp_f32_e32 v1, v1
	s_nop 1
	v_cvt_pk_bf16_f32 v149, v0, v1
	v_add_f32_e32 v0, 1.0, v2
	v_add_f32_e32 v1, 1.0, v3
	v_mul_f32_e32 v2, 0xbfb8aa3b, v40
	v_mul_f32_e32 v3, 0xbfb8aa3b, v41
	v_exp_f32_e32 v2, v2
	v_exp_f32_e32 v3, v3
	v_rcp_f32_e32 v0, v0
	v_rcp_f32_e32 v1, v1
	s_nop 1
	v_cvt_pk_bf16_f32 v150, v0, v1
	v_add_f32_e32 v0, 1.0, v2
	v_add_f32_e32 v1, 1.0, v3
	v_mul_f32_e32 v2, 0xbfb8aa3b, v42
	v_mul_f32_e32 v3, 0xbfb8aa3b, v43
	v_exp_f32_e32 v2, v2
	v_exp_f32_e32 v3, v3
	v_rcp_f32_e32 v0, v0
	v_rcp_f32_e32 v1, v1
	s_nop 1
	v_cvt_pk_bf16_f32 v146, v0, v1
	v_add_f32_e32 v0, 1.0, v2
	v_add_f32_e32 v1, 1.0, v3
	v_mul_f32_e32 v2, 0xbfb8aa3b, v36
	v_mul_f32_e32 v3, 0xbfb8aa3b, v37
	v_exp_f32_e32 v2, v2
	v_exp_f32_e32 v3, v3
	v_rcp_f32_e32 v0, v0
	v_rcp_f32_e32 v1, v1
	s_nop 1
	v_cvt_pk_bf16_f32 v148, v0, v1
	v_add_f32_e32 v0, 1.0, v2
	v_add_f32_e32 v1, 1.0, v3
	v_mul_f32_e32 v2, 0xbfb8aa3b, v38
	v_mul_f32_e32 v3, 0xbfb8aa3b, v39
	s_waitcnt vmcnt(14)
	v_mul_f32_e32 v4, 0xbfb8aa3b, v24
	v_mul_f32_e32 v5, 0xbfb8aa3b, v25
	v_mul_f32_e32 v6, 0xbfb8aa3b, v26
	v_mul_f32_e32 v7, 0xbfb8aa3b, v27
	v_exp_f32_e32 v2, v2
	v_exp_f32_e32 v3, v3
	v_exp_f32_e32 v4, v4
	v_exp_f32_e32 v5, v5
	v_exp_f32_e32 v6, v6
	v_exp_f32_e32 v7, v7
	v_add_f32_e32 v2, 1.0, v2
	v_add_f32_e32 v3, 1.0, v3
	v_add_f32_e32 v4, 1.0, v4
	v_add_f32_e32 v5, 1.0, v5
	v_add_f32_e32 v6, 1.0, v6
	v_add_f32_e32 v7, 1.0, v7
	v_rcp_f32_e32 v0, v0
	v_rcp_f32_e32 v1, v1
	v_rcp_f32_e32 v2, v2
	v_rcp_f32_e32 v3, v3
	v_rcp_f32_e32 v4, v4
	v_rcp_f32_e32 v5, v5
	v_rcp_f32_e32 v6, v6
	v_rcp_f32_e32 v7, v7
	s_mov_b64 s[18:19], -1
	s_and_b64 vcc, exec, s[16:17]
	s_nop 1
	v_cvt_pk_bf16_f32 v147, v0, v1
	s_nop 1
	v_cvt_pk_bf16_f32 v145, v2, v3
	s_nop 1
	v_cvt_pk_bf16_f32 v144, v4, v5
	s_nop 1
	v_cvt_pk_bf16_f32 v143, v6, v7
	s_cbranch_vccz .LBB0_227
	s_waitcnt vmcnt(7)
	v_mov_b32_e32 v46, v192
	s_movk_i32 s7, 0x70
	v_ashrrev_i32_e32 v32, 3, v46
	v_ashrrev_i32_e32 v33, 31, v32
	v_lshlrev_b64 v[0:1], 12, v[32:33]
	v_lshlrev_b32_e32 v4, 4, v46
	v_lshl_add_u64 v[2:3], s[8:9], 0, v[0:1]
	v_and_b32_e32 v176, 0x70, v4
	v_lshl_add_u64 v[138:139], v[2:3], 0, v[176:177]
	v_lshl_add_u64 v[0:1], s[10:11], 0, v[0:1]
	v_add_co_u32_e32 v34, vcc, 0x20000, v138
	v_lshl_add_u64 v[140:141], v[0:1], 0, v[176:177]
	s_nop 0
	v_addc_co_u32_e32 v35, vcc, 0, v139, vcc
	v_add_co_u32_e32 v36, vcc, 0x20000, v140
	global_load_dwordx4 v[0:3], v[138:139], off
	global_load_dwordx4 v[4:7], v[140:141], off
	v_addc_co_u32_e32 v37, vcc, 0, v141, vcc
	v_add_co_u32_e32 v38, vcc, s33, v138
	global_load_dwordx4 v[8:11], v[34:35], off
	global_load_dwordx4 v[12:15], v[36:37], off
	v_addc_co_u32_e32 v39, vcc, 0, v139, vcc
	v_add_co_u32_e32 v40, vcc, s33, v140
	global_load_dwordx4 v[16:19], v[38:39], off
	s_nop 0
	v_addc_co_u32_e32 v41, vcc, 0, v141, vcc
	v_add_co_u32_e32 v42, vcc, 0x60000, v138
	global_load_dwordx4 v[20:23], v[40:41], off
	s_nop 0
	v_addc_co_u32_e32 v43, vcc, 0, v139, vcc
	v_add_co_u32_e32 v44, vcc, 0x60000, v140
	global_load_dwordx4 v[24:27], v[42:43], off
	s_nop 0
	v_addc_co_u32_e32 v45, vcc, 0, v141, vcc
	global_load_dwordx4 v[28:31], v[44:45], off
	global_load_dwordx4 v[64:67], v[138:139], off offset:128
	global_load_dwordx4 v[68:71], v[140:141], off offset:128
	global_load_dwordx4 v[72:75], v[34:35], off offset:128
	global_load_dwordx4 v[76:79], v[36:37], off offset:128
	global_load_dwordx4 v[80:83], v[38:39], off offset:128
	global_load_dwordx4 v[84:87], v[40:41], off offset:128
	global_load_dwordx4 v[88:91], v[42:43], off offset:128
	global_load_dwordx4 v[92:95], v[44:45], off offset:128
	s_barrier
	global_load_dwordx4 v[96:99], v[138:139], off offset:256
	global_load_dwordx4 v[100:103], v[140:141], off offset:256
	global_load_dwordx4 v[104:107], v[34:35], off offset:256
	global_load_dwordx4 v[108:111], v[36:37], off offset:256
	global_load_dwordx4 v[112:115], v[38:39], off offset:256
	global_load_dwordx4 v[116:119], v[40:41], off offset:256
	global_load_dwordx4 v[120:123], v[42:43], off offset:256
	global_load_dwordx4 v[124:127], v[44:45], off offset:256
	s_waitcnt vmcnt(30)
	v_lshlrev_b32_e32 v51, 7, v32
	v_lshrrev_b32_e32 v32, 1, v32
	v_xor_b32_e32 v32, v32, v46
	v_lshlrev_b32_e32 v32, 4, v32
	v_lshrrev_b32_e32 v33, 4, v46
	v_bfe_u32 v47, v46, 4, 2
	v_bfe_u32 v48, v46, 1, 3
	v_and_or_b32 v175, v32, s7, v51
	v_lshlrev_b32_e32 v49, 6, v46
	v_lshlrev_b32_e32 v50, 7, v46
	v_bitop3_b32 v33, v33, v48, 3 bitop3:0x6c
	v_and_b32_e32 v49, 0xffffe000, v49
	v_and_b32_e32 v52, 0x780, v50
	v_and_b32_e32 v50, 0x2000, v50
	v_lshlrev_b32_e32 v33, 4, v33
	v_or_b32_e32 v46, v33, v49
	s_mov_b32 s7, -2
	v_add_u32_e32 v176, v46, v52
	s_waitcnt vmcnt(23)
	ds_write_b128 v175, v[0:3]
	s_waitcnt vmcnt(22)
	ds_write_b128 v175, v[4:7] offset:16384
	s_waitcnt vmcnt(21)
	ds_write_b128 v175, v[8:11] offset:4096
	s_waitcnt vmcnt(20)
	ds_write_b128 v175, v[12:15] offset:20480
	s_waitcnt vmcnt(19)
	ds_write_b128 v175, v[16:19] offset:8192
	s_waitcnt vmcnt(18)
	ds_write_b128 v175, v[20:23] offset:24576
	s_waitcnt vmcnt(17)
	ds_write_b128 v175, v[24:27] offset:12288
	s_waitcnt vmcnt(16)
	ds_write_b128 v175, v[28:31] offset:28672
	v_bitop3_b32 v0, v47, v48, 4 bitop3:0x36
	v_lshlrev_b32_e32 v0, 4, v0
	v_or_b32_e32 v1, v33, v50
	v_or_b32_e32 v2, v0, v49
	v_or_b32_e32 v3, v0, v50
	v_mov_b32_e32 v0, 0
	v_add_u32_e32 v178, v1, v52
	v_add_u32_e32 v179, v2, v52
	v_add_u32_e32 v180, v3, v52
	v_mov_b32_e32 v1, v0
	v_mov_b32_e32 v2, v0
	v_mov_b32_e32 v3, v0
	v_mov_b32_e32 v4, v0
	v_mov_b32_e32 v5, v0
	v_mov_b32_e32 v6, v0
	v_mov_b32_e32 v7, v0
	v_mov_b32_e32 v8, v0
	v_mov_b32_e32 v9, v0
	v_mov_b32_e32 v10, v0
	v_mov_b32_e32 v11, v0
	v_mov_b32_e32 v12, v0
	v_mov_b32_e32 v13, v0
	v_mov_b32_e32 v14, v0
	v_mov_b32_e32 v15, v0
	v_mov_b32_e32 v16, v0
	v_mov_b32_e32 v17, v0
	v_mov_b32_e32 v18, v0
	v_mov_b32_e32 v19, v0
	v_mov_b32_e32 v20, v0
	v_mov_b32_e32 v21, v0
	v_mov_b32_e32 v22, v0
	v_mov_b32_e32 v23, v0
	v_mov_b32_e32 v24, v0
	v_mov_b32_e32 v25, v0
	v_mov_b32_e32 v26, v0
	v_mov_b32_e32 v27, v0
	v_mov_b32_e32 v28, v0
	v_mov_b32_e32 v29, v0
	v_mov_b32_e32 v30, v0
	v_mov_b32_e32 v31, v0
	v_mov_b32_e32 v32, v0
	v_mov_b32_e32 v33, v0
	v_mov_b32_e32 v34, v0
	v_mov_b32_e32 v35, v0
	v_mov_b32_e32 v36, v0
	v_mov_b32_e32 v37, v0
	v_mov_b32_e32 v38, v0
	v_mov_b32_e32 v39, v0
	v_mov_b32_e32 v40, v0
	v_mov_b32_e32 v41, v0
	v_mov_b32_e32 v42, v0
	v_mov_b32_e32 v43, v0
	v_mov_b32_e32 v44, v0
	v_mov_b32_e32 v45, v0
	v_mov_b32_e32 v46, v0
	v_mov_b32_e32 v47, v0
	v_mov_b32_e32 v48, v0
	v_mov_b32_e32 v49, v0
	v_mov_b32_e32 v50, v0
	v_mov_b32_e32 v51, v0
	v_mov_b32_e32 v52, v0
	v_mov_b32_e32 v53, v0
	v_mov_b32_e32 v54, v0
	v_mov_b32_e32 v55, v0
	v_mov_b32_e32 v56, v0
	v_mov_b32_e32 v57, v0
	v_mov_b32_e32 v58, v0
	v_mov_b32_e32 v59, v0
	v_mov_b32_e32 v60, v0
	v_mov_b32_e32 v61, v0
	v_mov_b32_e32 v62, v0
	v_mov_b32_e32 v63, v0
	s_waitcnt lgkmcnt(0)
	s_barrier

.Lxk_225:
	ds_read_b128 v[194:197], v179
	ds_read_b128 v[198:201], v179 offset:2048
	ds_read_b128 v[202:205], v179 offset:4096
	ds_read_b128 v[206:209], v179 offset:6144
	ds_read_b128 v[210:213], v180 offset:16384
	ds_read_b128 v[214:217], v180 offset:18432
	ds_read_b128 v[244:247], v180 offset:20480
	ds_read_b128 v[248:251], v180 offset:22528
	s_waitcnt lgkmcnt(8)
	v_mfma_f32_16x16x32_bf16 v[60:63], v[228:231], v[182:185], v[60:63]
	s_add_i32 s7, s7, 2
	v_mfma_f32_16x16x32_bf16 v[56:59], v[232:235], v[182:185], v[56:59]
	s_min_u32 s18, s7, 28
	v_mfma_f32_16x16x32_bf16 v[52:55], v[236:239], v[182:185], v[52:55]
	s_lshl_b32 s56, s18, 7
	v_mfma_f32_16x16x32_bf16 v[48:51], v[240:243], v[182:185], v[48:51]
	s_min_u32 s18, s7, 27
	s_waitcnt vmcnt(15)
	v_mfma_f32_16x16x32_bf16 v[44:47], v[228:231], v[186:189], v[44:47]
	ds_write_b128 v175, v[64:67] offset:32768
	v_mfma_f32_16x16x32_bf16 v[40:43], v[232:235], v[186:189], v[40:43]
	s_waitcnt vmcnt(14)
	v_mfma_f32_16x16x32_bf16 v[36:39], v[236:239], v[186:189], v[36:39]
	ds_write_b128 v175, v[68:71] offset:49152
	v_mfma_f32_16x16x32_bf16 v[32:35], v[240:243], v[186:189], v[32:35]
	s_waitcnt vmcnt(13)
	ds_write_b128 v175, v[72:75] offset:36864
	v_mfma_f32_16x16x32_bf16 v[28:31], v[228:231], v[220:223], v[28:31]
	s_waitcnt vmcnt(12)
	v_mfma_f32_16x16x32_bf16 v[24:27], v[232:235], v[220:223], v[24:27]
	ds_write_b128 v175, v[76:79] offset:53248
	v_mfma_f32_16x16x32_bf16 v[20:23], v[236:239], v[220:223], v[20:23]
	s_waitcnt vmcnt(11)
	v_mfma_f32_16x16x32_bf16 v[16:19], v[240:243], v[220:223], v[16:19]
	ds_write_b128 v175, v[80:83] offset:40960
	s_waitcnt vmcnt(10)
	v_mfma_f32_16x16x32_bf16 v[12:15], v[228:231], v[224:227], v[12:15]
	ds_write_b128 v175, v[84:87] offset:57344
	v_mfma_f32_16x16x32_bf16 v[8:11], v[232:235], v[224:227], v[8:11]
	s_waitcnt vmcnt(9)
	v_mfma_f32_16x16x32_bf16 v[4:7], v[236:239], v[224:227], v[4:7]
	ds_write_b128 v175, v[88:91] offset:45056
	v_mfma_f32_16x16x32_bf16 v[0:3], v[240:243], v[224:227], v[0:3]
	s_waitcnt vmcnt(8)
	ds_write_b128 v175, v[92:95] offset:61440
	s_waitcnt lgkmcnt(8)
	v_mfma_f32_16x16x32_bf16 v[60:63], v[210:213], v[194:197], v[60:63]
	v_mfma_f32_16x16x32_bf16 v[56:59], v[214:217], v[194:197], v[56:59]
	v_mfma_f32_16x16x32_bf16 v[52:55], v[244:247], v[194:197], v[52:55]
	v_mfma_f32_16x16x32_bf16 v[48:51], v[248:251], v[194:197], v[48:51]
	s_waitcnt lgkmcnt(0)
	s_barrier
	ds_read_b128 v[182:185], v176 offset:32768
	ds_read_b128 v[186:189], v176 offset:34816
	ds_read_b128 v[220:223], v176 offset:36864
	ds_read_b128 v[224:227], v176 offset:38912
	ds_read_b128 v[228:231], v178 offset:49152
	ds_read_b128 v[232:235], v178 offset:51200
	ds_read_b128 v[236:239], v178 offset:53248
	ds_read_b128 v[240:243], v178 offset:55296
	v_lshl_add_u64 v[88:89], v[138:139], 0, s[56:57]
	v_add_co_u32_e32 v72, vcc, s46, v88
	v_lshl_add_u64 v[92:93], v[140:141], 0, s[56:57]
	s_nop 0
	v_addc_co_u32_e32 v73, vcc, 0, v89, vcc
	v_add_co_u32_e32 v76, vcc, s46, v92
	v_mfma_f32_16x16x32_bf16 v[44:47], v[210:213], v[198:201], v[44:47]
	global_load_dwordx4 v[64:67], v[88:89], off offset:384
	v_mfma_f32_16x16x32_bf16 v[40:43], v[214:217], v[198:201], v[40:43]
	global_load_dwordx4 v[68:71], v[92:93], off offset:384
	v_addc_co_u32_e32 v77, vcc, 0, v93, vcc
	v_mfma_f32_16x16x32_bf16 v[36:39], v[244:247], v[198:201], v[36:39]
	v_add_co_u32_e32 v80, vcc, s33, v88
	v_mfma_f32_16x16x32_bf16 v[32:35], v[248:251], v[198:201], v[32:35]
	s_nop 0
	v_addc_co_u32_e32 v81, vcc, 0, v89, vcc
	v_add_co_u32_e32 v84, vcc, s33, v92
	v_mfma_f32_16x16x32_bf16 v[28:31], v[210:213], v[202:205], v[28:31]
	s_nop 0
	v_addc_co_u32_e32 v85, vcc, 0, v93, vcc
	v_add_co_u32_e32 v88, vcc, s48, v88
	v_mfma_f32_16x16x32_bf16 v[24:27], v[214:217], v[202:205], v[24:27]
	s_nop 0
	v_addc_co_u32_e32 v89, vcc, 0, v89, vcc
	v_mfma_f32_16x16x32_bf16 v[20:23], v[244:247], v[202:205], v[20:23]
	v_add_co_u32_e32 v92, vcc, s48, v92
	s_nop 1
	s_nop 0
	v_addc_co_u32_e32 v93, vcc, 0, v93, vcc
	v_mfma_f32_16x16x32_bf16 v[16:19], v[248:251], v[202:205], v[16:19]
	global_load_dwordx4 v[72:75], v[72:73], off offset:384
	v_mfma_f32_16x16x32_bf16 v[12:15], v[210:213], v[206:209], v[12:15]
	global_load_dwordx4 v[76:79], v[76:77], off offset:384
	s_lshl_b32 s56, s18, 7
	v_mfma_f32_16x16x32_bf16 v[8:11], v[214:217], v[206:209], v[8:11]
	global_load_dwordx4 v[80:83], v[80:81], off offset:384
	v_mfma_f32_16x16x32_bf16 v[4:7], v[244:247], v[206:209], v[4:7]
	global_load_dwordx4 v[84:87], v[84:85], off offset:384
	s_cmp_lt_u32 s7, 30
	v_mfma_f32_16x16x32_bf16 v[0:3], v[248:251], v[206:209], v[0:3]
	global_load_dwordx4 v[88:91], v[88:89], off offset:384
	global_load_dwordx4 v[92:95], v[92:93], off offset:384
	ds_read_b128 v[194:197], v179 offset:32768
	ds_read_b128 v[198:201], v179 offset:34816
	ds_read_b128 v[202:205], v179 offset:36864
	ds_read_b128 v[206:209], v179 offset:38912
	ds_read_b128 v[210:213], v180 offset:49152
	ds_read_b128 v[214:217], v180 offset:51200
	ds_read_b128 v[244:247], v180 offset:53248
	ds_read_b128 v[248:251], v180 offset:55296
	s_waitcnt lgkmcnt(8)
	v_mfma_f32_16x16x32_bf16 v[60:63], v[228:231], v[182:185], v[60:63]
	s_waitcnt vmcnt(15)
	v_mfma_f32_16x16x32_bf16 v[56:59], v[232:235], v[182:185], v[56:59]
	ds_write_b128 v175, v[96:99]
	v_mfma_f32_16x16x32_bf16 v[52:55], v[236:239], v[182:185], v[52:55]
	s_waitcnt vmcnt(14)
	v_mfma_f32_16x16x32_bf16 v[48:51], v[240:243], v[182:185], v[48:51]
	ds_write_b128 v175, v[100:103] offset:16384
	v_mfma_f32_16x16x32_bf16 v[44:47], v[228:231], v[186:189], v[44:47]
	s_waitcnt vmcnt(13)
	v_mfma_f32_16x16x32_bf16 v[40:43], v[232:235], v[186:189], v[40:43]
	ds_write_b128 v175, v[104:107] offset:4096
	v_mfma_f32_16x16x32_bf16 v[36:39], v[236:239], v[186:189], v[36:39]
	s_waitcnt vmcnt(12)
	v_mfma_f32_16x16x32_bf16 v[32:35], v[240:243], v[186:189], v[32:35]
	ds_write_b128 v175, v[108:111] offset:20480
	v_mfma_f32_16x16x32_bf16 v[28:31], v[228:231], v[220:223], v[28:31]
	s_waitcnt vmcnt(11)
	v_mfma_f32_16x16x32_bf16 v[24:27], v[232:235], v[220:223], v[24:27]
	ds_write_b128 v175, v[112:115] offset:8192
	v_mfma_f32_16x16x32_bf16 v[20:23], v[236:239], v[220:223], v[20:23]
	s_waitcnt vmcnt(10)
	v_mfma_f32_16x16x32_bf16 v[16:19], v[240:243], v[220:223], v[16:19]
	ds_write_b128 v175, v[116:119] offset:24576
	v_mfma_f32_16x16x32_bf16 v[12:15], v[228:231], v[224:227], v[12:15]
	s_waitcnt vmcnt(9)
	v_mfma_f32_16x16x32_bf16 v[8:11], v[232:235], v[224:227], v[8:11]
	ds_write_b128 v175, v[120:123] offset:12288
	v_mfma_f32_16x16x32_bf16 v[4:7], v[236:239], v[224:227], v[4:7]
	s_waitcnt vmcnt(8)
	v_mfma_f32_16x16x32_bf16 v[0:3], v[240:243], v[224:227], v[0:3]
	ds_write_b128 v175, v[124:127] offset:28672
	s_waitcnt lgkmcnt(8)
	v_mfma_f32_16x16x32_bf16 v[60:63], v[210:213], v[194:197], v[60:63]
	v_mfma_f32_16x16x32_bf16 v[56:59], v[214:217], v[194:197], v[56:59]
	v_mfma_f32_16x16x32_bf16 v[52:55], v[244:247], v[194:197], v[52:55]
	v_mfma_f32_16x16x32_bf16 v[48:51], v[248:251], v[194:197], v[48:51]
	s_waitcnt lgkmcnt(0)
	s_barrier
	ds_read_b128 v[182:185], v176
	ds_read_b128 v[186:189], v176 offset:2048
	ds_read_b128 v[220:223], v176 offset:4096
	ds_read_b128 v[224:227], v176 offset:6144
	ds_read_b128 v[228:231], v178 offset:16384
	ds_read_b128 v[232:235], v178 offset:18432
	ds_read_b128 v[236:239], v178 offset:20480
	ds_read_b128 v[240:243], v178 offset:22528
	v_lshl_add_u64 v[120:121], v[138:139], 0, s[56:57]
	v_add_co_u32_e32 v104, vcc, s46, v120
	v_lshl_add_u64 v[124:125], v[140:141], 0, s[56:57]
	s_nop 0
	v_addc_co_u32_e32 v105, vcc, 0, v121, vcc
	v_add_co_u32_e32 v108, vcc, s46, v124
	v_mfma_f32_16x16x32_bf16 v[44:47], v[210:213], v[198:201], v[44:47]
	global_load_dwordx4 v[96:99], v[120:121], off offset:512
	global_load_dwordx4 v[100:103], v[124:125], off offset:512
	v_mfma_f32_16x16x32_bf16 v[40:43], v[214:217], v[198:201], v[40:43]
	v_addc_co_u32_e32 v109, vcc, 0, v125, vcc
	v_add_co_u32_e32 v112, vcc, s33, v120
	v_mfma_f32_16x16x32_bf16 v[36:39], v[244:247], v[198:201], v[36:39]
	global_load_dwordx4 v[104:107], v[104:105], off offset:512
	v_mfma_f32_16x16x32_bf16 v[32:35], v[248:251], v[198:201], v[32:35]
	s_nop 0
	v_addc_co_u32_e32 v113, vcc, 0, v121, vcc
	v_mfma_f32_16x16x32_bf16 v[28:31], v[210:213], v[202:205], v[28:31]
	v_add_co_u32_e32 v116, vcc, s33, v124
	global_load_dwordx4 v[108:111], v[108:109], off offset:512
	v_mfma_f32_16x16x32_bf16 v[24:27], v[214:217], v[202:205], v[24:27]
	s_nop 0
	v_mfma_f32_16x16x32_bf16 v[20:23], v[244:247], v[202:205], v[20:23]
	v_addc_co_u32_e32 v117, vcc, 0, v125, vcc
	v_add_co_u32_e32 v120, vcc, s48, v120
	v_mfma_f32_16x16x32_bf16 v[16:19], v[248:251], v[202:205], v[16:19]
	global_load_dwordx4 v[112:115], v[112:113], off offset:512
	s_nop 0
	v_mfma_f32_16x16x32_bf16 v[12:15], v[210:213], v[206:209], v[12:15]
	v_addc_co_u32_e32 v121, vcc, 0, v121, vcc
	v_mfma_f32_16x16x32_bf16 v[8:11], v[214:217], v[206:209], v[8:11]
	v_add_co_u32_e32 v124, vcc, s48, v124
	global_load_dwordx4 v[116:119], v[116:117], off offset:512
	v_mfma_f32_16x16x32_bf16 v[4:7], v[244:247], v[206:209], v[4:7]
	s_nop 0
	v_addc_co_u32_e32 v125, vcc, 0, v125, vcc
	v_mfma_f32_16x16x32_bf16 v[0:3], v[248:251], v[206:209], v[0:3]
	global_load_dwordx4 v[120:123], v[120:121], off offset:512
	global_load_dwordx4 v[124:127], v[124:125], off offset:512
	s_cbranch_scc1 .Lxk_225
	s_waitcnt vmcnt(0) lgkmcnt(0)
	s_mov_b64 s[18:19], 0

.Lxk_229:
	ds_read_b128 v[194:197], v179
	ds_read_b128 v[198:201], v179 offset:2048
	ds_read_b128 v[202:205], v179 offset:4096
	ds_read_b128 v[206:209], v179 offset:6144
	ds_read_b128 v[210:213], v180 offset:16384
	ds_read_b128 v[214:217], v180 offset:18432
	ds_read_b128 v[244:247], v180 offset:20480
	ds_read_b128 v[248:251], v180 offset:22528
	s_waitcnt lgkmcnt(8)
	v_mfma_f32_16x16x32_bf16 v[60:63], v[228:231], v[182:185], v[60:63]
	s_add_i32 s7, s7, 2
	v_mfma_f32_16x16x32_bf16 v[56:59], v[232:235], v[182:185], v[56:59]
	s_min_u32 s18, s7, 16
	v_mfma_f32_16x16x32_bf16 v[52:55], v[236:239], v[182:185], v[52:55]
	s_lshl_b32 s56, s18, 7
	v_mfma_f32_16x16x32_bf16 v[48:51], v[240:243], v[182:185], v[48:51]
	s_min_u32 s18, s7, 15
	s_waitcnt vmcnt(15)
	v_mfma_f32_16x16x32_bf16 v[44:47], v[228:231], v[186:189], v[44:47]
	ds_write_b128 v175, v[64:67] offset:32768
	v_mfma_f32_16x16x32_bf16 v[40:43], v[232:235], v[186:189], v[40:43]
	s_waitcnt vmcnt(14)
	v_mfma_f32_16x16x32_bf16 v[36:39], v[236:239], v[186:189], v[36:39]
	ds_write_b128 v175, v[68:71] offset:49152
	v_mfma_f32_16x16x32_bf16 v[32:35], v[240:243], v[186:189], v[32:35]
	s_waitcnt vmcnt(13)
	ds_write_b128 v175, v[72:75] offset:36864
	v_mfma_f32_16x16x32_bf16 v[28:31], v[228:231], v[220:223], v[28:31]
	s_waitcnt vmcnt(12)
	v_mfma_f32_16x16x32_bf16 v[24:27], v[232:235], v[220:223], v[24:27]
	ds_write_b128 v175, v[76:79] offset:53248
	v_mfma_f32_16x16x32_bf16 v[20:23], v[236:239], v[220:223], v[20:23]
	s_waitcnt vmcnt(11)
	v_mfma_f32_16x16x32_bf16 v[16:19], v[240:243], v[220:223], v[16:19]
	ds_write_b128 v175, v[80:83] offset:40960
	s_waitcnt vmcnt(10)
	v_mfma_f32_16x16x32_bf16 v[12:15], v[228:231], v[224:227], v[12:15]
	ds_write_b128 v175, v[84:87] offset:57344
	v_mfma_f32_16x16x32_bf16 v[8:11], v[232:235], v[224:227], v[8:11]
	s_waitcnt vmcnt(9)
	v_mfma_f32_16x16x32_bf16 v[4:7], v[236:239], v[224:227], v[4:7]
	ds_write_b128 v175, v[88:91] offset:45056
	v_mfma_f32_16x16x32_bf16 v[0:3], v[240:243], v[224:227], v[0:3]
	s_waitcnt vmcnt(8)
	ds_write_b128 v175, v[92:95] offset:61440
	s_waitcnt lgkmcnt(8)
	v_mfma_f32_16x16x32_bf16 v[60:63], v[210:213], v[194:197], v[60:63]
	v_mfma_f32_16x16x32_bf16 v[56:59], v[214:217], v[194:197], v[56:59]
	v_mfma_f32_16x16x32_bf16 v[52:55], v[244:247], v[194:197], v[52:55]
	v_mfma_f32_16x16x32_bf16 v[48:51], v[248:251], v[194:197], v[48:51]
	s_waitcnt lgkmcnt(0)
	s_barrier
	ds_read_b128 v[182:185], v176 offset:32768
	ds_read_b128 v[186:189], v176 offset:34816
	ds_read_b128 v[220:223], v176 offset:36864
	ds_read_b128 v[224:227], v176 offset:38912
	ds_read_b128 v[228:231], v178 offset:49152
	ds_read_b128 v[232:235], v178 offset:51200
	ds_read_b128 v[236:239], v178 offset:53248
	ds_read_b128 v[240:243], v178 offset:55296
	v_lshl_add_u64 v[88:89], v[138:139], 0, s[56:57]
	v_add_co_u32_e32 v72, vcc, s49, v88
	v_lshl_add_u64 v[92:93], v[140:141], 0, s[56:57]
	s_nop 0
	v_addc_co_u32_e32 v73, vcc, 0, v89, vcc
	v_add_co_u32_e32 v76, vcc, s49, v92
	v_mfma_f32_16x16x32_bf16 v[44:47], v[210:213], v[198:201], v[44:47]
	global_load_dwordx4 v[64:67], v[88:89], off offset:384
	v_mfma_f32_16x16x32_bf16 v[40:43], v[214:217], v[198:201], v[40:43]
	global_load_dwordx4 v[68:71], v[92:93], off offset:384
	v_addc_co_u32_e32 v77, vcc, 0, v93, vcc
	v_mfma_f32_16x16x32_bf16 v[36:39], v[244:247], v[198:201], v[36:39]
	v_add_co_u32_e32 v80, vcc, s50, v88
	v_mfma_f32_16x16x32_bf16 v[32:35], v[248:251], v[198:201], v[32:35]
	s_nop 0
	v_addc_co_u32_e32 v81, vcc, 0, v89, vcc
	v_add_co_u32_e32 v84, vcc, s50, v92
	v_mfma_f32_16x16x32_bf16 v[28:31], v[210:213], v[202:205], v[28:31]
	s_nop 0
	v_addc_co_u32_e32 v85, vcc, 0, v93, vcc
	v_add_co_u32_e32 v88, vcc, s51, v88
	v_mfma_f32_16x16x32_bf16 v[24:27], v[214:217], v[202:205], v[24:27]
	s_nop 0
	v_addc_co_u32_e32 v89, vcc, 0, v89, vcc
	v_mfma_f32_16x16x32_bf16 v[20:23], v[244:247], v[202:205], v[20:23]
	v_add_co_u32_e32 v92, vcc, s51, v92
	s_nop 1
	s_nop 0
	v_addc_co_u32_e32 v93, vcc, 0, v93, vcc
	v_mfma_f32_16x16x32_bf16 v[16:19], v[248:251], v[202:205], v[16:19]
	global_load_dwordx4 v[72:75], v[72:73], off offset:384
	v_mfma_f32_16x16x32_bf16 v[12:15], v[210:213], v[206:209], v[12:15]
	global_load_dwordx4 v[76:79], v[76:77], off offset:384
	s_lshl_b32 s56, s18, 7
	v_mfma_f32_16x16x32_bf16 v[8:11], v[214:217], v[206:209], v[8:11]
	global_load_dwordx4 v[80:83], v[80:81], off offset:384
	v_mfma_f32_16x16x32_bf16 v[4:7], v[244:247], v[206:209], v[4:7]
	global_load_dwordx4 v[84:87], v[84:85], off offset:384
	s_cmp_gt_u32 s7, 17
	v_mfma_f32_16x16x32_bf16 v[0:3], v[248:251], v[206:209], v[0:3]
	global_load_dwordx4 v[88:91], v[88:89], off offset:384
	global_load_dwordx4 v[92:95], v[92:93], off offset:384
	ds_read_b128 v[194:197], v179 offset:32768
	ds_read_b128 v[198:201], v179 offset:34816
	ds_read_b128 v[202:205], v179 offset:36864
	ds_read_b128 v[206:209], v179 offset:38912
	ds_read_b128 v[210:213], v180 offset:49152
	ds_read_b128 v[214:217], v180 offset:51200
	ds_read_b128 v[244:247], v180 offset:53248
	ds_read_b128 v[248:251], v180 offset:55296
	s_waitcnt lgkmcnt(8)
	v_mfma_f32_16x16x32_bf16 v[60:63], v[228:231], v[182:185], v[60:63]
	s_waitcnt vmcnt(15)
	v_mfma_f32_16x16x32_bf16 v[56:59], v[232:235], v[182:185], v[56:59]
	ds_write_b128 v175, v[96:99]
	v_mfma_f32_16x16x32_bf16 v[52:55], v[236:239], v[182:185], v[52:55]
	s_waitcnt vmcnt(14)
	v_mfma_f32_16x16x32_bf16 v[48:51], v[240:243], v[182:185], v[48:51]
	ds_write_b128 v175, v[100:103] offset:16384
	v_mfma_f32_16x16x32_bf16 v[44:47], v[228:231], v[186:189], v[44:47]
	s_waitcnt vmcnt(13)
	v_mfma_f32_16x16x32_bf16 v[40:43], v[232:235], v[186:189], v[40:43]
	ds_write_b128 v175, v[104:107] offset:4096
	v_mfma_f32_16x16x32_bf16 v[36:39], v[236:239], v[186:189], v[36:39]
	s_waitcnt vmcnt(12)
	v_mfma_f32_16x16x32_bf16 v[32:35], v[240:243], v[186:189], v[32:35]
	ds_write_b128 v175, v[108:111] offset:20480
	v_mfma_f32_16x16x32_bf16 v[28:31], v[228:231], v[220:223], v[28:31]
	s_waitcnt vmcnt(11)
	v_mfma_f32_16x16x32_bf16 v[24:27], v[232:235], v[220:223], v[24:27]
	ds_write_b128 v175, v[112:115] offset:8192
	v_mfma_f32_16x16x32_bf16 v[20:23], v[236:239], v[220:223], v[20:23]
	s_waitcnt vmcnt(10)
	v_mfma_f32_16x16x32_bf16 v[16:19], v[240:243], v[220:223], v[16:19]
	ds_write_b128 v175, v[116:119] offset:24576
	v_mfma_f32_16x16x32_bf16 v[12:15], v[228:231], v[224:227], v[12:15]
	s_waitcnt vmcnt(9)
	v_mfma_f32_16x16x32_bf16 v[8:11], v[232:235], v[224:227], v[8:11]
	ds_write_b128 v175, v[120:123] offset:12288
	v_mfma_f32_16x16x32_bf16 v[4:7], v[236:239], v[224:227], v[4:7]
	s_waitcnt vmcnt(8)
	v_mfma_f32_16x16x32_bf16 v[0:3], v[240:243], v[224:227], v[0:3]
	ds_write_b128 v175, v[124:127] offset:28672
	s_waitcnt lgkmcnt(8)
	v_mfma_f32_16x16x32_bf16 v[60:63], v[210:213], v[194:197], v[60:63]
	v_mfma_f32_16x16x32_bf16 v[56:59], v[214:217], v[194:197], v[56:59]
	v_mfma_f32_16x16x32_bf16 v[52:55], v[244:247], v[194:197], v[52:55]
	v_mfma_f32_16x16x32_bf16 v[48:51], v[248:251], v[194:197], v[48:51]
	s_waitcnt lgkmcnt(0)
	s_barrier
	ds_read_b128 v[182:185], v176
	ds_read_b128 v[186:189], v176 offset:2048
	ds_read_b128 v[220:223], v176 offset:4096
	ds_read_b128 v[224:227], v176 offset:6144
	ds_read_b128 v[228:231], v178 offset:16384
	ds_read_b128 v[232:235], v178 offset:18432
	ds_read_b128 v[236:239], v178 offset:20480
	ds_read_b128 v[240:243], v178 offset:22528
	v_lshl_add_u64 v[120:121], v[138:139], 0, s[56:57]
	v_add_co_u32_e32 v104, vcc, s49, v120
	v_lshl_add_u64 v[124:125], v[140:141], 0, s[56:57]
	s_nop 0
	v_addc_co_u32_e32 v105, vcc, 0, v121, vcc
	v_add_co_u32_e32 v108, vcc, s49, v124
	v_mfma_f32_16x16x32_bf16 v[44:47], v[210:213], v[198:201], v[44:47]
	global_load_dwordx4 v[96:99], v[120:121], off offset:512
	global_load_dwordx4 v[100:103], v[124:125], off offset:512
	v_mfma_f32_16x16x32_bf16 v[40:43], v[214:217], v[198:201], v[40:43]
	v_addc_co_u32_e32 v109, vcc, 0, v125, vcc
	v_add_co_u32_e32 v112, vcc, s50, v120
	v_mfma_f32_16x16x32_bf16 v[36:39], v[244:247], v[198:201], v[36:39]
	global_load_dwordx4 v[104:107], v[104:105], off offset:512
	v_mfma_f32_16x16x32_bf16 v[32:35], v[248:251], v[198:201], v[32:35]
	s_nop 0
	v_addc_co_u32_e32 v113, vcc, 0, v121, vcc
	v_mfma_f32_16x16x32_bf16 v[28:31], v[210:213], v[202:205], v[28:31]
	v_add_co_u32_e32 v116, vcc, s50, v124
	global_load_dwordx4 v[108:111], v[108:109], off offset:512
	v_mfma_f32_16x16x32_bf16 v[24:27], v[214:217], v[202:205], v[24:27]
	s_nop 0
	v_mfma_f32_16x16x32_bf16 v[20:23], v[244:247], v[202:205], v[20:23]
	v_addc_co_u32_e32 v117, vcc, 0, v125, vcc
	v_add_co_u32_e32 v120, vcc, s51, v120
	v_mfma_f32_16x16x32_bf16 v[16:19], v[248:251], v[202:205], v[16:19]
	global_load_dwordx4 v[112:115], v[112:113], off offset:512
	s_nop 0
	v_mfma_f32_16x16x32_bf16 v[12:15], v[210:213], v[206:209], v[12:15]
	v_addc_co_u32_e32 v121, vcc, 0, v121, vcc
	v_mfma_f32_16x16x32_bf16 v[8:11], v[214:217], v[206:209], v[8:11]
	v_add_co_u32_e32 v124, vcc, s51, v124
	global_load_dwordx4 v[116:119], v[116:117], off offset:512
	v_mfma_f32_16x16x32_bf16 v[4:7], v[244:247], v[206:209], v[4:7]
	s_nop 0
	v_addc_co_u32_e32 v125, vcc, 0, v125, vcc
	v_mfma_f32_16x16x32_bf16 v[0:3], v[248:251], v[206:209], v[0:3]
	global_load_dwordx4 v[120:123], v[120:121], off offset:512
	global_load_dwordx4 v[124:127], v[124:125], off offset:512
	s_cbranch_scc0 .Lxk_229
	s_waitcnt vmcnt(0) lgkmcnt(0)
